# v30 plus the lagging half's extra barrier at the end of the tile header (prologue stagger and closing wr0 barriers dropped)
# baseline (speedup 1.0000x reference)
; #define PG8_STAGE(bufoff, gbase, voff) do { _Pragma("unroll") for (int _i = 0; _i < 2; ++_i) \
;         __builtin_amdgcn_global_load_lds((const unsigned*)((const char*)(gbase) + (voff)[_i]), (LAS unsigned*)(lds + (bufoff) + ldsw + _i * 8192), 16, 0, 0); } while (0)
; #define PG8_LDA(dst, b, h) do { _Pragma("unroll") for (int m = 0; m < 4; ++m) _Pragma("unroll") for (int k = 0; k < 2; ++k) dst[m][k] = *(const LAS h16x8*)(lds + PG8_SA(b, h) + aoff + m * 2048 + k * 1024); } while (0)
; #define PG8_LDB(dst, b, h) do { _Pragma("unroll") for (int n = 0; n < 2; ++n) _Pragma("unroll") for (int k = 0; k < 2; ++k) dst[n][k] = *(const LAS h16x8*)(lds + PG8_SB(b, h) + boff + n * 2048 + k * 1024); } while (0)
; #define PG8_MMA(ai, bj, At, Bt_) do { __builtin_amdgcn_s_setprio(1); _Pragma("unroll") for (int m = 0; m < 4; ++m) _Pragma("unroll") for (int n = 0; n < 2; ++n) _Pragma("unroll") for (int k = 0; k < 2; ++k) \
;         acc[ai][bj][m][n] = __builtin_amdgcn_mfma_f32_16x16x32_f16(Bt_[n][k], At[m][k], acc[ai][bj][m][n], 0, 0, 0); __builtin_amdgcn_s_setprio(0); } while (0)
; #define PG8_WAIT_V(n) asm volatile("s_waitcnt vmcnt(" #n ")" ::: "memory")
; #define PG8_WAIT_L(n) asm volatile("s_waitcnt lgkmcnt(" #n ")" ::: "memory")
; #define PG8_BAR __builtin_amdgcn_s_barrier()
; #define PG8_SCHED __builtin_amdgcn_sched_barrier(0)
; template <class Epi, class AMap>
; __device__ __forceinline__ void gemm_phase(LAS unsigned char* lds, const AMap am, const int lda, const h16* Bt, const int ldb, const int M, const int N, const int K, const Epi& E) {
;     ...
;             PG8_LDB(B0, 0, 0); PG8_SCHED; PG8_LDA(At, 0, 0); PG8_STAGE(PG8_SA(1, 1), a1 + hstepA, voffA);
;             PG8_WAIT_L(8); PG8_BAR; PG8_WAIT_L(0); PG8_MMA(0, 0, At, B0); PG8_BAR; PG8_SCHED;
;             PG8_LDB(B1, 0, 1); PG8_STAGE(PG8_SB(0, 0), b2, voffB);
;             PG8_BAR; PG8_WAIT_L(0); PG8_MMA(0, 1, At, B1); PG8_BAR;
;             PG8_LDA(At, 0, 1); PG8_STAGE(PG8_SA(0, 0), a2, voffA);
;             PG8_BAR; PG8_WAIT_L(0); PG8_MMA(1, 0, At, B0); PG8_BAR; PG8_SCHED;
;             PG8_STAGE(PG8_SB(0, 1), b2 + hstepB, voffB);
;             PG8_WAIT_V(6); PG8_BAR; PG8_MMA(1, 1, At, B1); PG8_BAR;
.Lgy0:
.Lg4p_61:
	s_add_u32 s26, s22, 0x100
	s_addc_u32 s27, s23, 0
	s_add_i32 s51, 0, 0x10000
	v_add_u32_e32 v144, s51, v147
	ds_read_b128 v[140:143], v144
	ds_read_b128 v[150:153], v144 offset:1024
	ds_read_b128 v[154:157], v144 offset:2048
	ds_read_b128 v[158:161], v144 offset:3072
	s_cmpk_eq_i32 s29, 0x52
	s_cselect_b32 s45, s1, s27
	s_cselect_b32 s44, s0, s26
	s_cselect_b32 s43, s41, s21
	s_cselect_b32 s42, s40, s20
	v_lshl_add_u64 v[144:145], s[22:23], 0, v[136:137]
	s_add_i32 m0, s63, 0xc000
	ds_read_b128 v[162:165], v149
	ds_read_b128 v[166:169], v149 offset:1024
	ds_read_b128 v[170:173], v149 offset:2048
	ds_read_b128 v[174:177], v149 offset:3072
	ds_read_b128 v[178:181], v149 offset:4096
	ds_read_b128 v[182:185], v149 offset:5120
	ds_read_b128 v[186:189], v149 offset:6144
	ds_read_b128 v[190:193], v149 offset:7168
	global_load_lds_dwordx4 v[144:145], off
	v_lshl_add_u64 v[144:145], s[22:23], 0, v[138:139]
	s_add_i32 m0, s63, 0xe000
	s_nop 0
	global_load_lds_dwordx4 v[144:145], off
	s_waitcnt lgkmcnt(11)
	s_add_i32 s60, 0, 0x14000
	v_add_u32_e32 v144, s60, v147
	s_add_i32 s22, s51, s48
	ds_read_b128 v[194:197], v144
	ds_read_b128 v[198:201], v144 offset:1024
	ds_read_b128 v[202:205], v144 offset:2048
	ds_read_b128 v[220:223], v144 offset:3072
	s_waitcnt vmcnt(40) lgkmcnt(0)
	s_barrier
	v_mfma_f32_16x16x32_f16 v[126:129], v[140:143], v[162:165], 0
	v_mfma_f32_16x16x32_f16 v[122:125], v[154:157], v[162:165], 0
	v_mfma_f32_16x16x32_f16 v[110:113], v[140:143], v[170:173], 0
	v_mfma_f32_16x16x32_f16 v[106:109], v[154:157], v[170:173], 0
	v_mfma_f32_16x16x32_f16 v[94:97], v[140:143], v[178:181], 0
	v_mfma_f32_16x16x32_f16 v[90:93], v[154:157], v[178:181], 0
	v_mfma_f32_16x16x32_f16 v[78:81], v[140:143], v[186:189], 0
	v_mfma_f32_16x16x32_f16 v[74:77], v[154:157], v[186:189], 0
	v_mfma_f32_16x16x32_f16 v[126:129], v[150:153], v[166:169], v[126:129]
	v_mfma_f32_16x16x32_f16 v[122:125], v[158:161], v[166:169], v[122:125]
	v_mfma_f32_16x16x32_f16 v[110:113], v[150:153], v[174:177], v[110:113]
	v_mfma_f32_16x16x32_f16 v[106:109], v[158:161], v[174:177], v[106:109]
	v_mfma_f32_16x16x32_f16 v[94:97], v[150:153], v[182:185], v[94:97]
	v_mfma_f32_16x16x32_f16 v[90:93], v[158:161], v[182:185], v[90:93]
	v_mfma_f32_16x16x32_f16 v[78:81], v[150:153], v[190:193], v[78:81]
	v_mfma_f32_16x16x32_f16 v[74:77], v[158:161], v[190:193], v[74:77]
	v_mfma_f32_16x16x32_f16 v[118:121], v[194:197], v[162:165], 0
	v_mfma_f32_16x16x32_f16 v[114:117], v[202:205], v[162:165], 0
	v_mfma_f32_16x16x32_f16 v[102:105], v[194:197], v[170:173], 0
	v_mfma_f32_16x16x32_f16 v[98:101], v[202:205], v[170:173], 0
	v_mfma_f32_16x16x32_f16 v[86:89], v[194:197], v[178:181], 0
	v_mfma_f32_16x16x32_f16 v[82:85], v[202:205], v[178:181], 0
	v_mfma_f32_16x16x32_f16 v[70:73], v[194:197], v[186:189], 0
	v_mfma_f32_16x16x32_f16 v[66:69], v[202:205], v[186:189], 0
	v_mfma_f32_16x16x32_f16 v[118:121], v[198:201], v[166:169], v[118:121]
	v_mfma_f32_16x16x32_f16 v[114:117], v[220:223], v[166:169], v[114:117]
	v_mfma_f32_16x16x32_f16 v[102:105], v[198:201], v[174:177], v[102:105]
	v_mfma_f32_16x16x32_f16 v[98:101], v[220:223], v[174:177], v[98:101]
	v_mfma_f32_16x16x32_f16 v[86:89], v[198:201], v[182:185], v[86:89]
	v_mfma_f32_16x16x32_f16 v[82:85], v[220:223], v[182:185], v[82:85]
	v_mfma_f32_16x16x32_f16 v[70:73], v[198:201], v[190:193], v[70:73]
	v_mfma_f32_16x16x32_f16 v[66:69], v[220:223], v[190:193], v[66:69]
	s_barrier
	v_lshl_add_u64 v[144:145], s[42:43], 0, v[0:1]
	s_mov_b32 m0, s22
	v_lshl_add_u64 v[206:207], s[42:43], 0, v[134:135]
	global_load_lds_dwordx4 v[144:145], off
	s_add_i32 m0, s22, 0x2000
	s_nop 0
	global_load_lds_dwordx4 v[206:207], off
	s_mov_b32 m0, s63
	v_lshl_add_u64 v[212:213], s[44:45], 0, v[130:131]
	ds_read_b128 v[162:165], v149 offset:16384
	ds_read_b128 v[166:169], v149 offset:17408
	ds_read_b128 v[170:173], v149 offset:18432
	ds_read_b128 v[174:177], v149 offset:19456
	ds_read_b128 v[178:181], v149 offset:20480
	ds_read_b128 v[182:185], v149 offset:21504
	ds_read_b128 v[186:189], v149 offset:22528
	ds_read_b128 v[190:193], v149 offset:23552
	global_load_lds_dwordx4 v[212:213], off
	v_lshl_add_u64 v[214:215], s[44:45], 0, v[132:133]
	s_mov_b32 m0, s64
	s_nop 0
	global_load_lds_dwordx4 v[214:215], off
	s_add_u32 s22, s42, 0x158000
	s_addc_u32 s23, s43, 0
	s_add_i32 s51, s60, s48
	v_lshl_add_u64 v[232:233], s[22:23], 0, v[0:1]
	s_mov_b32 m0, s51
	s_nop 0
	global_load_lds_dwordx4 v[232:233], off
	v_lshl_add_u64 v[232:233], s[22:23], 0, v[134:135]
	s_add_i32 m0, s51, 0x2000
	s_nop 0
	global_load_lds_dwordx4 v[232:233], off
	s_waitcnt vmcnt(8) lgkmcnt(0)
	s_barrier
; #define PG8_STAGE(bufoff, gbase, voff) do { _Pragma("unroll") for (int _i = 0; _i < 2; ++_i) \
;         __builtin_amdgcn_global_load_lds((const unsigned*)((const char*)(gbase) + (voff)[_i]), (LAS unsigned*)(lds + (bufoff) + ldsw + _i * 8192), 16, 0, 0); } while (0)
; #define PG8_LDA(dst, b, h) do { _Pragma("unroll") for (int m = 0; m < 4; ++m) _Pragma("unroll") for (int k = 0; k < 2; ++k) dst[m][k] = *(const LAS h16x8*)(lds + PG8_SA(b, h) + aoff + m * 2048 + k * 1024); } while (0)
; #define PG8_LDB(dst, b, h) do { _Pragma("unroll") for (int n = 0; n < 2; ++n) _Pragma("unroll") for (int k = 0; k < 2; ++k) dst[n][k] = *(const LAS h16x8*)(lds + PG8_SB(b, h) + boff + n * 2048 + k * 1024); } while (0)
; #define PG8_MMA(ai, bj, At, Bt_) do { __builtin_amdgcn_s_setprio(1); _Pragma("unroll") for (int m = 0; m < 4; ++m) _Pragma("unroll") for (int n = 0; n < 2; ++n) _Pragma("unroll") for (int k = 0; k < 2; ++k) \
;         acc[ai][bj][m][n] = __builtin_amdgcn_mfma_f32_16x16x32_f16(Bt_[n][k], At[m][k], acc[ai][bj][m][n], 0, 0, 0); __builtin_amdgcn_s_setprio(0); } while (0)
; #define PG8_WAIT_V(n) asm volatile("s_waitcnt vmcnt(" #n ")" ::: "memory")
; #define PG8_WAIT_L(n) asm volatile("s_waitcnt lgkmcnt(" #n ")" ::: "memory")
; #define PG8_BAR __builtin_amdgcn_s_barrier()
; #define PG8_SCHED __builtin_amdgcn_sched_barrier(0)
; template <class Epi, class AMap>
; __device__ __forceinline__ void gemm_phase(LAS unsigned char* lds, const AMap am, const int lda, const h16* Bt, const int ldb, const int M, const int N, const int K, const Epi& E) {
;     ...
;             PG8_WAIT_V(6); PG8_BAR; PG8_MMA(1, 1, At, B1); PG8_BAR;
;             PG8_LDB(B0, 1, 0); PG8_SCHED; PG8_LDA(At, 1, 0); PG8_STAGE(PG8_SA(0, 1), a2 + hstepA, voffA);
;             PG8_WAIT_L(8); PG8_BAR; PG8_WAIT_L(0); PG8_MMA(0, 0, At, B0); PG8_BAR; PG8_SCHED;
;             PG8_LDB(B1, 1, 1); PG8_STAGE(PG8_SB(1, 0), b3, voffB);
;             PG8_BAR; PG8_WAIT_L(0); PG8_MMA(0, 1, At, B1); PG8_BAR;
	v_mfma_f32_16x16x32_f16 v[62:65], v[140:143], v[162:165], 0
	v_mfma_f32_16x16x32_f16 v[58:61], v[154:157], v[162:165], 0
	v_mfma_f32_16x16x32_f16 v[46:49], v[140:143], v[170:173], 0
	v_mfma_f32_16x16x32_f16 v[42:45], v[154:157], v[170:173], 0
	v_mfma_f32_16x16x32_f16 v[30:33], v[140:143], v[178:181], 0
	v_mfma_f32_16x16x32_f16 v[26:29], v[154:157], v[178:181], 0
	v_mfma_f32_16x16x32_f16 v[14:17], v[140:143], v[186:189], 0
	v_mfma_f32_16x16x32_f16 v[10:13], v[154:157], v[186:189], 0
	v_mfma_f32_16x16x32_f16 v[62:65], v[150:153], v[166:169], v[62:65]
	v_mfma_f32_16x16x32_f16 v[58:61], v[158:161], v[166:169], v[58:61]
	v_mfma_f32_16x16x32_f16 v[46:49], v[150:153], v[174:177], v[46:49]
	v_mfma_f32_16x16x32_f16 v[42:45], v[158:161], v[174:177], v[42:45]
	v_mfma_f32_16x16x32_f16 v[30:33], v[150:153], v[182:185], v[30:33]
	v_mfma_f32_16x16x32_f16 v[26:29], v[158:161], v[182:185], v[26:29]
	v_mfma_f32_16x16x32_f16 v[14:17], v[150:153], v[190:193], v[14:17]
	v_mfma_f32_16x16x32_f16 v[10:13], v[158:161], v[190:193], v[10:13]
	v_mfma_f32_16x16x32_f16 v[54:57], v[194:197], v[162:165], 0
	v_mfma_f32_16x16x32_f16 v[50:53], v[202:205], v[162:165], 0
	v_mfma_f32_16x16x32_f16 v[38:41], v[194:197], v[170:173], 0
	v_mfma_f32_16x16x32_f16 v[34:37], v[202:205], v[170:173], 0
	v_mfma_f32_16x16x32_f16 v[22:25], v[194:197], v[178:181], 0
	v_mfma_f32_16x16x32_f16 v[18:21], v[202:205], v[178:181], 0
	v_mfma_f32_16x16x32_f16 v[6:9], v[194:197], v[186:189], 0
	v_mfma_f32_16x16x32_f16 v[2:5], v[202:205], v[186:189], 0
	v_mfma_f32_16x16x32_f16 v[54:57], v[198:201], v[166:169], v[54:57]
	v_mfma_f32_16x16x32_f16 v[50:53], v[220:223], v[166:169], v[50:53]
	v_mfma_f32_16x16x32_f16 v[38:41], v[198:201], v[174:177], v[38:41]
	v_mfma_f32_16x16x32_f16 v[34:37], v[220:223], v[174:177], v[34:37]
	v_mfma_f32_16x16x32_f16 v[22:25], v[198:201], v[182:185], v[22:25]
	v_mfma_f32_16x16x32_f16 v[18:21], v[220:223], v[182:185], v[18:21]
	v_mfma_f32_16x16x32_f16 v[6:9], v[198:201], v[190:193], v[6:9]
	v_mfma_f32_16x16x32_f16 v[2:5], v[220:223], v[190:193], v[2:5]
	s_barrier
	s_add_i32 s51, 0, 0x18000
	v_add_u32_e32 v234, s51, v147
	ds_read_b128 v[140:143], v234
	ds_read_b128 v[150:153], v234 offset:1024
	ds_read_b128 v[154:157], v234 offset:2048
	ds_read_b128 v[158:161], v234 offset:3072
	s_add_u32 s22, s44, 0x158000
	s_addc_u32 s23, s45, 0
	s_mov_b32 m0, s65
	v_lshl_add_u64 v[232:233], s[22:23], 0, v[130:131]
	ds_read_b128 v[162:165], v149 offset:32768
	ds_read_b128 v[166:169], v149 offset:33792
	ds_read_b128 v[170:173], v149 offset:34816
	ds_read_b128 v[174:177], v149 offset:35840
	ds_read_b128 v[178:181], v149 offset:36864
	ds_read_b128 v[182:185], v149 offset:37888
	ds_read_b128 v[186:189], v149 offset:38912
	ds_read_b128 v[190:193], v149 offset:39936
	global_load_lds_dwordx4 v[232:233], off
	v_lshl_add_u64 v[232:233], s[22:23], 0, v[132:133]
	s_mov_b32 m0, s68
	s_nop 0
	global_load_lds_dwordx4 v[232:233], off
	s_waitcnt lgkmcnt(11)
	s_add_i32 s44, 0, 0x1c000
	s_add_i32 s22, s51, s48
	v_add_u32_e32 v216, s44, v147
	v_lshl_add_u64 v[144:145], v[144:145], 0, s[92:93]
	s_mov_b32 m0, s22
	ds_read_b128 v[194:197], v216
	ds_read_b128 v[198:201], v216 offset:1024
	ds_read_b128 v[202:205], v216 offset:2048
	ds_read_b128 v[220:223], v216 offset:3072
	s_waitcnt vmcnt(8) lgkmcnt(0)
	s_barrier
	v_mfma_f32_16x16x32_f16 v[126:129], v[140:143], v[162:165], v[126:129]
	v_mfma_f32_16x16x32_f16 v[122:125], v[154:157], v[162:165], v[122:125]
	v_mfma_f32_16x16x32_f16 v[110:113], v[140:143], v[170:173], v[110:113]
	v_mfma_f32_16x16x32_f16 v[106:109], v[154:157], v[170:173], v[106:109]
	v_mfma_f32_16x16x32_f16 v[94:97], v[140:143], v[178:181], v[94:97]
	v_mfma_f32_16x16x32_f16 v[90:93], v[154:157], v[178:181], v[90:93]
	v_mfma_f32_16x16x32_f16 v[78:81], v[140:143], v[186:189], v[78:81]
	v_mfma_f32_16x16x32_f16 v[74:77], v[154:157], v[186:189], v[74:77]
	v_mfma_f32_16x16x32_f16 v[126:129], v[150:153], v[166:169], v[126:129]
	v_mfma_f32_16x16x32_f16 v[122:125], v[158:161], v[166:169], v[122:125]
	v_mfma_f32_16x16x32_f16 v[110:113], v[150:153], v[174:177], v[110:113]
	v_mfma_f32_16x16x32_f16 v[106:109], v[158:161], v[174:177], v[106:109]
	v_mfma_f32_16x16x32_f16 v[94:97], v[150:153], v[182:185], v[94:97]
	v_mfma_f32_16x16x32_f16 v[90:93], v[158:161], v[182:185], v[90:93]
	v_mfma_f32_16x16x32_f16 v[78:81], v[150:153], v[190:193], v[78:81]
	v_mfma_f32_16x16x32_f16 v[74:77], v[158:161], v[190:193], v[74:77]
	v_mfma_f32_16x16x32_f16 v[118:121], v[194:197], v[162:165], v[118:121]
	v_mfma_f32_16x16x32_f16 v[114:117], v[202:205], v[162:165], v[114:117]
	v_mfma_f32_16x16x32_f16 v[102:105], v[194:197], v[170:173], v[102:105]
	v_mfma_f32_16x16x32_f16 v[98:101], v[202:205], v[170:173], v[98:101]
	v_mfma_f32_16x16x32_f16 v[86:89], v[194:197], v[178:181], v[86:89]
	v_mfma_f32_16x16x32_f16 v[82:85], v[202:205], v[178:181], v[82:85]
	v_mfma_f32_16x16x32_f16 v[70:73], v[194:197], v[186:189], v[70:73]
	v_mfma_f32_16x16x32_f16 v[66:69], v[202:205], v[186:189], v[66:69]
	v_mfma_f32_16x16x32_f16 v[118:121], v[198:201], v[166:169], v[118:121]
	v_mfma_f32_16x16x32_f16 v[114:117], v[220:223], v[166:169], v[114:117]
	v_mfma_f32_16x16x32_f16 v[102:105], v[198:201], v[174:177], v[102:105]
	v_mfma_f32_16x16x32_f16 v[98:101], v[220:223], v[174:177], v[98:101]
	v_mfma_f32_16x16x32_f16 v[86:89], v[198:201], v[182:185], v[86:89]
	v_mfma_f32_16x16x32_f16 v[82:85], v[220:223], v[182:185], v[82:85]
	v_mfma_f32_16x16x32_f16 v[70:73], v[198:201], v[190:193], v[70:73]
	v_mfma_f32_16x16x32_f16 v[66:69], v[220:223], v[190:193], v[66:69]
	s_barrier
; #define PG8_STAGE(bufoff, gbase, voff) do { _Pragma("unroll") for (int _i = 0; _i < 2; ++_i) \
;         __builtin_amdgcn_global_load_lds((const unsigned*)((const char*)(gbase) + (voff)[_i]), (LAS unsigned*)(lds + (bufoff) + ldsw + _i * 8192), 16, 0, 0); } while (0)
; #define PG8_LDA(dst, b, h) do { _Pragma("unroll") for (int m = 0; m < 4; ++m) _Pragma("unroll") for (int k = 0; k < 2; ++k) dst[m][k] = *(const LAS h16x8*)(lds + PG8_SA(b, h) + aoff + m * 2048 + k * 1024); } while (0)
; #define PG8_MMA(ai, bj, At, Bt_) do { __builtin_amdgcn_s_setprio(1); _Pragma("unroll") for (int m = 0; m < 4; ++m) _Pragma("unroll") for (int n = 0; n < 2; ++n) _Pragma("unroll") for (int k = 0; k < 2; ++k) \
;         acc[ai][bj][m][n] = __builtin_amdgcn_mfma_f32_16x16x32_f16(Bt_[n][k], At[m][k], acc[ai][bj][m][n], 0, 0, 0); __builtin_amdgcn_s_setprio(0); } while (0)
; #define PG8_WAIT_V(n) asm volatile("s_waitcnt vmcnt(" #n ")" ::: "memory")
; #define PG8_WAIT_L(n) asm volatile("s_waitcnt lgkmcnt(" #n ")" ::: "memory")
; #define PG8_BAR __builtin_amdgcn_s_barrier()
; #define PG8_SCHED __builtin_amdgcn_sched_barrier(0)
; template <class Epi, class AMap>
; __device__ __forceinline__ void gemm_phase(LAS unsigned char* lds, const AMap am, const int lda, const h16* Bt, const int ldb, const int M, const int N, const int K, const Epi& E) {
;     ...
;             PG8_LDA(At, 1, 1); PG8_STAGE(PG8_SA(1, 0), a3, voffA);
;             PG8_BAR; PG8_WAIT_L(0); PG8_MMA(1, 0, At, B0); PG8_BAR; PG8_SCHED;
;             PG8_STAGE(PG8_SB(1, 1), b3 + hstepB, voffB);
;             PG8_WAIT_V(6); PG8_BAR; PG8_MMA(1, 1, At, B1); PG8_BAR;
	global_load_lds_dwordx4 v[144:145], off
	v_lshl_add_u64 v[144:145], v[206:207], 0, s[92:93]
	s_add_i32 m0, s22, 0x2000
	s_nop 0
	global_load_lds_dwordx4 v[144:145], off
	s_mov_b32 m0, s69
	v_lshl_add_u64 v[144:145], v[212:213], 0, s[92:93]
	ds_read_b128 v[162:165], v149 offset:49152
	ds_read_b128 v[166:169], v149 offset:50176
	ds_read_b128 v[170:173], v149 offset:51200
	ds_read_b128 v[174:177], v149 offset:52224
	ds_read_b128 v[178:181], v149 offset:53248
	ds_read_b128 v[182:185], v149 offset:54272
	ds_read_b128 v[186:189], v149 offset:55296
	ds_read_b128 v[190:193], v149 offset:56320
	global_load_lds_dwordx4 v[144:145], off
	v_lshl_add_u64 v[144:145], v[214:215], 0, s[92:93]
	s_mov_b32 m0, s70
	s_nop 0
	global_load_lds_dwordx4 v[144:145], off
	s_add_u32 s22, s42, 0x158080
	s_addc_u32 s23, s43, 0
	s_add_i32 s42, s44, s48
	v_lshl_add_u64 v[232:233], s[22:23], 0, v[0:1]
	s_mov_b32 m0, s42
	s_nop 0
	global_load_lds_dwordx4 v[232:233], off
	v_lshl_add_u64 v[232:233], s[22:23], 0, v[134:135]
	s_add_i32 m0, s42, 0x2000
	s_nop 0
	global_load_lds_dwordx4 v[232:233], off
	s_add_i32 s29, s29, 2
	s_add_u32 s20, s20, 0x100
	s_addc_u32 s21, s21, 0
	s_cmpk_gt_u32 s29, 0x53
	s_mov_b64 s[22:23], s[26:27]
	s_waitcnt vmcnt(8) lgkmcnt(0)
	s_barrier
	v_mfma_f32_16x16x32_f16 v[62:65], v[140:143], v[162:165], v[62:65]
	v_mfma_f32_16x16x32_f16 v[58:61], v[154:157], v[162:165], v[58:61]
	v_mfma_f32_16x16x32_f16 v[46:49], v[140:143], v[170:173], v[46:49]
	v_mfma_f32_16x16x32_f16 v[42:45], v[154:157], v[170:173], v[42:45]
	v_mfma_f32_16x16x32_f16 v[30:33], v[140:143], v[178:181], v[30:33]
	v_mfma_f32_16x16x32_f16 v[26:29], v[154:157], v[178:181], v[26:29]
	v_mfma_f32_16x16x32_f16 v[14:17], v[140:143], v[186:189], v[14:17]
	v_mfma_f32_16x16x32_f16 v[10:13], v[154:157], v[186:189], v[10:13]
	v_mfma_f32_16x16x32_f16 v[62:65], v[150:153], v[166:169], v[62:65]
	v_mfma_f32_16x16x32_f16 v[58:61], v[158:161], v[166:169], v[58:61]
	v_mfma_f32_16x16x32_f16 v[46:49], v[150:153], v[174:177], v[46:49]
	v_mfma_f32_16x16x32_f16 v[42:45], v[158:161], v[174:177], v[42:45]
	v_mfma_f32_16x16x32_f16 v[30:33], v[150:153], v[182:185], v[30:33]
	v_mfma_f32_16x16x32_f16 v[26:29], v[158:161], v[182:185], v[26:29]
	v_mfma_f32_16x16x32_f16 v[14:17], v[150:153], v[190:193], v[14:17]
	v_mfma_f32_16x16x32_f16 v[10:13], v[158:161], v[190:193], v[10:13]
	v_mfma_f32_16x16x32_f16 v[54:57], v[194:197], v[162:165], v[54:57]
	v_mfma_f32_16x16x32_f16 v[50:53], v[202:205], v[162:165], v[50:53]
	v_mfma_f32_16x16x32_f16 v[38:41], v[194:197], v[170:173], v[38:41]
	v_mfma_f32_16x16x32_f16 v[34:37], v[202:205], v[170:173], v[34:37]
	v_mfma_f32_16x16x32_f16 v[22:25], v[194:197], v[178:181], v[22:25]
	v_mfma_f32_16x16x32_f16 v[18:21], v[202:205], v[178:181], v[18:21]
	v_mfma_f32_16x16x32_f16 v[6:9], v[194:197], v[186:189], v[6:9]
	v_mfma_f32_16x16x32_f16 v[2:5], v[202:205], v[186:189], v[2:5]
	v_mfma_f32_16x16x32_f16 v[54:57], v[198:201], v[166:169], v[54:57]
	v_mfma_f32_16x16x32_f16 v[50:53], v[220:223], v[166:169], v[50:53]
	v_mfma_f32_16x16x32_f16 v[38:41], v[198:201], v[174:177], v[38:41]
	v_mfma_f32_16x16x32_f16 v[34:37], v[220:223], v[174:177], v[34:37]
	v_mfma_f32_16x16x32_f16 v[22:25], v[198:201], v[182:185], v[22:25]
	v_mfma_f32_16x16x32_f16 v[18:21], v[220:223], v[182:185], v[18:21]
	v_mfma_f32_16x16x32_f16 v[6:9], v[198:201], v[190:193], v[6:9]
	v_mfma_f32_16x16x32_f16 v[2:5], v[220:223], v[190:193], v[2:5]
	s_barrier
	s_cbranch_scc1 .Lg4x_61

; #define PG8_STAGE(bufoff, gbase, voff) do { _Pragma("unroll") for (int _i = 0; _i < 2; ++_i) \
;         __builtin_amdgcn_global_load_lds((const unsigned*)((const char*)(gbase) + (voff)[_i]), (LAS unsigned*)(lds + (bufoff) + ldsw + _i * 8192), 16, 0, 0); } while (0)
; #define PG8_LDA(dst, b, h) do { _Pragma("unroll") for (int m = 0; m < 4; ++m) _Pragma("unroll") for (int k = 0; k < 2; ++k) dst[m][k] = *(const LAS h16x8*)(lds + PG8_SA(b, h) + aoff + m * 2048 + k * 1024); } while (0)
; #define PG8_LDB(dst, b, h) do { _Pragma("unroll") for (int n = 0; n < 2; ++n) _Pragma("unroll") for (int k = 0; k < 2; ++k) dst[n][k] = *(const LAS h16x8*)(lds + PG8_SB(b, h) + boff + n * 2048 + k * 1024); } while (0)
; #define PG8_MMA(ai, bj, At, Bt_) do { __builtin_amdgcn_s_setprio(1); _Pragma("unroll") for (int m = 0; m < 4; ++m) _Pragma("unroll") for (int n = 0; n < 2; ++n) _Pragma("unroll") for (int k = 0; k < 2; ++k) \
;         acc[ai][bj][m][n] = __builtin_amdgcn_mfma_f32_16x16x32_f16(Bt_[n][k], At[m][k], acc[ai][bj][m][n], 0, 0, 0); __builtin_amdgcn_s_setprio(0); } while (0)
; #define PG8_WAIT_V(n) asm volatile("s_waitcnt vmcnt(" #n ")" ::: "memory")
; #define PG8_WAIT_L(n) asm volatile("s_waitcnt lgkmcnt(" #n ")" ::: "memory")
; #define PG8_BAR __builtin_amdgcn_s_barrier()
; #define PG8_SCHED __builtin_amdgcn_sched_barrier(0)
; template <class Epi, class AMap>
; __device__ __forceinline__ void gemm_phase(LAS unsigned char* lds, const AMap am, const int lda, const h16* Bt, const int ldb, const int M, const int N, const int K, const Epi& E) {
;     ...
;             PG8_LDB(B0, 0, 0); PG8_SCHED; PG8_LDA(At, 0, 0); PG8_STAGE(PG8_SA(1, 1), a1 + hstepA, voffA);
;             PG8_WAIT_L(8); PG8_BAR; PG8_WAIT_L(0); PG8_MMA(0, 0, At, B0); PG8_BAR; PG8_SCHED;
;             PG8_LDB(B1, 0, 1); PG8_STAGE(PG8_SB(0, 0), b2, voffB);
;             PG8_BAR; PG8_WAIT_L(0); PG8_MMA(0, 1, At, B1); PG8_BAR;
;             PG8_LDA(At, 0, 1); PG8_STAGE(PG8_SA(0, 0), a2, voffA);
;             PG8_BAR; PG8_WAIT_L(0); PG8_MMA(1, 0, At, B0); PG8_BAR; PG8_SCHED;
;             PG8_STAGE(PG8_SB(0, 1), b2 + hstepB, voffB);
;             PG8_WAIT_V(6); PG8_BAR; PG8_MMA(1, 1, At, B1); PG8_BAR;
.Lgy1:
.Lg4p_92:
	s_add_u32 s0, vcc_lo, 0xfff80080
	s_addc_u32 s1, vcc_hi, -1
	s_add_i32 s67, 0, 0x10000
	v_add_u32_e32 v226, s67, v169
	ds_read_b128 v[66:69], v226
	ds_read_b128 v[70:73], v226 offset:1024
	ds_read_b128 v[74:77], v226 offset:2048
	ds_read_b128 v[78:81], v226 offset:3072
	s_cmp_eq_u32 s60, 28
	s_cselect_b32 s27, s69, s1
	s_cselect_b32 s26, s29, s0
	s_cselect_b32 s49, s73, s66
	s_cselect_b32 s48, s20, s21
	v_lshl_add_u64 v[192:193], vcc, 0, v[172:173]
	s_add_i32 m0, s81, 0xc000
	ds_read_b128 v[90:93], v195
	ds_read_b128 v[94:97], v195 offset:1024
	ds_read_b128 v[98:101], v195 offset:2048
	ds_read_b128 v[102:105], v195 offset:3072
	ds_read_b128 v[176:179], v195 offset:4096
	ds_read_b128 v[180:183], v195 offset:5120
	ds_read_b128 v[184:187], v195 offset:6144
	ds_read_b128 v[188:191], v195 offset:7168
	global_load_lds_dwordx4 v[192:193], off
	v_lshl_add_u64 v[192:193], vcc, 0, v[174:175]
	s_add_i32 m0, s81, 0xe000
	s_nop 0
	global_load_lds_dwordx4 v[192:193], off
	s_waitcnt lgkmcnt(11)
	s_add_i32 s65, 0, 0x14000
	v_add_u32_e32 v192, s65, v169
	s_add_i32 s0, s67, s64
	ds_read_b128 v[196:199], v192
	ds_read_b128 v[200:203], v192 offset:1024
	ds_read_b128 v[204:207], v192 offset:2048
	ds_read_b128 v[220:223], v192 offset:3072
	s_waitcnt vmcnt(22) lgkmcnt(0)
	s_barrier
	v_mfma_f32_16x16x32_f16 v[158:161], v[66:69], v[90:93], 0
	v_mfma_f32_16x16x32_f16 v[154:157], v[74:77], v[90:93], 0
	v_mfma_f32_16x16x32_f16 v[142:145], v[66:69], v[98:101], 0
	v_mfma_f32_16x16x32_f16 v[134:137], v[74:77], v[98:101], 0
	v_mfma_f32_16x16x32_f16 v[126:129], v[66:69], v[176:179], 0
	v_mfma_f32_16x16x32_f16 v[118:121], v[74:77], v[176:179], 0
	v_mfma_f32_16x16x32_f16 v[110:113], v[66:69], v[184:187], 0
	v_mfma_f32_16x16x32_f16 v[106:109], v[74:77], v[184:187], 0
	v_mfma_f32_16x16x32_f16 v[158:161], v[70:73], v[94:97], v[158:161]
	v_mfma_f32_16x16x32_f16 v[154:157], v[78:81], v[94:97], v[154:157]
	v_mfma_f32_16x16x32_f16 v[142:145], v[70:73], v[102:105], v[142:145]
	v_mfma_f32_16x16x32_f16 v[134:137], v[78:81], v[102:105], v[134:137]
	v_mfma_f32_16x16x32_f16 v[126:129], v[70:73], v[180:183], v[126:129]
	v_mfma_f32_16x16x32_f16 v[118:121], v[78:81], v[180:183], v[118:121]
	v_mfma_f32_16x16x32_f16 v[110:113], v[70:73], v[188:191], v[110:113]
	v_mfma_f32_16x16x32_f16 v[106:109], v[78:81], v[188:191], v[106:109]
	v_mfma_f32_16x16x32_f16 v[150:153], v[196:199], v[90:93], 0
	v_mfma_f32_16x16x32_f16 v[146:149], v[204:207], v[90:93], 0
	v_mfma_f32_16x16x32_f16 v[150:153], v[200:203], v[94:97], v[150:153]
	v_mfma_f32_16x16x32_f16 v[146:149], v[220:223], v[94:97], v[146:149]
	v_mfma_f32_16x16x32_f16 v[138:141], v[196:199], v[98:101], 0
	v_mfma_f32_16x16x32_f16 v[130:133], v[204:207], v[98:101], 0
	v_mfma_f32_16x16x32_f16 v[114:117], v[204:207], v[176:179], 0
	v_mfma_f32_16x16x32_f16 v[86:89], v[196:199], v[184:187], 0
	v_mfma_f32_16x16x32_f16 v[82:85], v[204:207], v[184:187], 0
	v_mfma_f32_16x16x32_f16 v[138:141], v[200:203], v[102:105], v[138:141]
	v_mfma_f32_16x16x32_f16 v[130:133], v[220:223], v[102:105], v[130:133]
	v_mfma_f32_16x16x32_f16 v[122:125], v[196:199], v[176:179], 0
	v_mfma_f32_16x16x32_f16 v[114:117], v[220:223], v[180:183], v[114:117]
	v_mfma_f32_16x16x32_f16 v[86:89], v[200:203], v[188:191], v[86:89]
	v_mfma_f32_16x16x32_f16 v[82:85], v[220:223], v[188:191], v[82:85]
	v_mfma_f32_16x16x32_f16 v[122:125], v[200:203], v[180:183], v[122:125]
	s_barrier
	v_lshl_add_u64 v[192:193], s[48:49], 0, v[0:1]
	s_mov_b32 m0, s0
	v_lshl_add_u64 v[212:213], s[48:49], 0, v[162:163]
	global_load_lds_dwordx4 v[192:193], off
	s_add_i32 m0, s0, 0x2000
	s_nop 0
	global_load_lds_dwordx4 v[212:213], off
	s_mov_b32 m0, s81
	v_lshl_add_u64 v[214:215], s[26:27], 0, v[166:167]
	ds_read_b128 v[90:93], v195 offset:16384
	ds_read_b128 v[94:97], v195 offset:17408
	ds_read_b128 v[98:101], v195 offset:18432
	ds_read_b128 v[102:105], v195 offset:19456
	ds_read_b128 v[176:179], v195 offset:20480
	ds_read_b128 v[180:183], v195 offset:21504
	ds_read_b128 v[184:187], v195 offset:22528
	ds_read_b128 v[188:191], v195 offset:23552
	global_load_lds_dwordx4 v[214:215], off
	v_lshl_add_u64 v[216:217], s[26:27], 0, v[164:165]
	s_mov_b32 m0, s82
	s_nop 0
	global_load_lds_dwordx4 v[216:217], off
	s_add_u32 s0, s48, 0x80000
	s_addc_u32 s1, s49, 0
	s_add_i32 s65, s65, s64
	v_lshl_add_u64 v[224:225], s[0:1], 0, v[0:1]
	s_mov_b32 m0, s65
	s_nop 0
	global_load_lds_dwordx4 v[224:225], off
	v_lshl_add_u64 v[224:225], s[0:1], 0, v[162:163]
	s_add_i32 m0, s65, 0x2000
	s_nop 0
	global_load_lds_dwordx4 v[224:225], off
	s_waitcnt vmcnt(8) lgkmcnt(0)
	s_barrier
	v_mfma_f32_16x16x32_f16 v[62:65], v[66:69], v[90:93], 0
	v_mfma_f32_16x16x32_f16 v[58:61], v[74:77], v[90:93], 0
	v_mfma_f32_16x16x32_f16 v[46:49], v[66:69], v[98:101], 0
	v_mfma_f32_16x16x32_f16 v[38:41], v[74:77], v[98:101], 0
	v_mfma_f32_16x16x32_f16 v[30:33], v[66:69], v[176:179], 0
	v_mfma_f32_16x16x32_f16 v[22:25], v[74:77], v[176:179], 0
	v_mfma_f32_16x16x32_f16 v[14:17], v[66:69], v[184:187], 0
	v_mfma_f32_16x16x32_f16 v[10:13], v[74:77], v[184:187], 0
	v_mfma_f32_16x16x32_f16 v[62:65], v[70:73], v[94:97], v[62:65]
	v_mfma_f32_16x16x32_f16 v[58:61], v[78:81], v[94:97], v[58:61]
	v_mfma_f32_16x16x32_f16 v[46:49], v[70:73], v[102:105], v[46:49]
	v_mfma_f32_16x16x32_f16 v[38:41], v[78:81], v[102:105], v[38:41]
	v_mfma_f32_16x16x32_f16 v[30:33], v[70:73], v[180:183], v[30:33]
	v_mfma_f32_16x16x32_f16 v[22:25], v[78:81], v[180:183], v[22:25]
	v_mfma_f32_16x16x32_f16 v[14:17], v[70:73], v[188:191], v[14:17]
	v_mfma_f32_16x16x32_f16 v[10:13], v[78:81], v[188:191], v[10:13]
	v_mfma_f32_16x16x32_f16 v[54:57], v[196:199], v[90:93], 0
	v_mfma_f32_16x16x32_f16 v[50:53], v[204:207], v[90:93], 0
	v_mfma_f32_16x16x32_f16 v[42:45], v[196:199], v[98:101], 0
	v_mfma_f32_16x16x32_f16 v[34:37], v[204:207], v[98:101], 0
	v_mfma_f32_16x16x32_f16 v[26:29], v[196:199], v[176:179], 0
	v_mfma_f32_16x16x32_f16 v[18:21], v[204:207], v[176:179], 0
	v_mfma_f32_16x16x32_f16 v[6:9], v[196:199], v[184:187], 0
	v_mfma_f32_16x16x32_f16 v[2:5], v[204:207], v[184:187], 0
	v_mfma_f32_16x16x32_f16 v[54:57], v[200:203], v[94:97], v[54:57]
	v_mfma_f32_16x16x32_f16 v[50:53], v[220:223], v[94:97], v[50:53]
	v_mfma_f32_16x16x32_f16 v[42:45], v[200:203], v[102:105], v[42:45]
	v_mfma_f32_16x16x32_f16 v[34:37], v[220:223], v[102:105], v[34:37]
	v_mfma_f32_16x16x32_f16 v[26:29], v[200:203], v[180:183], v[26:29]
	v_mfma_f32_16x16x32_f16 v[18:21], v[220:223], v[180:183], v[18:21]
	v_mfma_f32_16x16x32_f16 v[6:9], v[200:203], v[188:191], v[6:9]
	v_mfma_f32_16x16x32_f16 v[2:5], v[220:223], v[188:191], v[2:5]
	s_barrier
; #define PG8_STAGE(bufoff, gbase, voff) do { _Pragma("unroll") for (int _i = 0; _i < 2; ++_i) \
;         __builtin_amdgcn_global_load_lds((const unsigned*)((const char*)(gbase) + (voff)[_i]), (LAS unsigned*)(lds + (bufoff) + ldsw + _i * 8192), 16, 0, 0); } while (0)
; #define PG8_LDA(dst, b, h) do { _Pragma("unroll") for (int m = 0; m < 4; ++m) _Pragma("unroll") for (int k = 0; k < 2; ++k) dst[m][k] = *(const LAS h16x8*)(lds + PG8_SA(b, h) + aoff + m * 2048 + k * 1024); } while (0)
; #define PG8_LDB(dst, b, h) do { _Pragma("unroll") for (int n = 0; n < 2; ++n) _Pragma("unroll") for (int k = 0; k < 2; ++k) dst[n][k] = *(const LAS h16x8*)(lds + PG8_SB(b, h) + boff + n * 2048 + k * 1024); } while (0)
; #define PG8_MMA(ai, bj, At, Bt_) do { __builtin_amdgcn_s_setprio(1); _Pragma("unroll") for (int m = 0; m < 4; ++m) _Pragma("unroll") for (int n = 0; n < 2; ++n) _Pragma("unroll") for (int k = 0; k < 2; ++k) \
;         acc[ai][bj][m][n] = __builtin_amdgcn_mfma_f32_16x16x32_f16(Bt_[n][k], At[m][k], acc[ai][bj][m][n], 0, 0, 0); __builtin_amdgcn_s_setprio(0); } while (0)
; #define PG8_WAIT_V(n) asm volatile("s_waitcnt vmcnt(" #n ")" ::: "memory")
; #define PG8_WAIT_L(n) asm volatile("s_waitcnt lgkmcnt(" #n ")" ::: "memory")
; #define PG8_BAR __builtin_amdgcn_s_barrier()
; #define PG8_SCHED __builtin_amdgcn_sched_barrier(0)
; template <class Epi, class AMap>
; __device__ __forceinline__ void gemm_phase(LAS unsigned char* lds, const AMap am, const int lda, const h16* Bt, const int ldb, const int M, const int N, const int K, const Epi& E) {
;     ...
;             PG8_WAIT_V(6); PG8_BAR; PG8_MMA(1, 1, At, B1); PG8_BAR;
;             PG8_LDB(B0, 1, 0); PG8_SCHED; PG8_LDA(At, 1, 0); PG8_STAGE(PG8_SA(0, 1), a2 + hstepA, voffA);
;             PG8_WAIT_L(8); PG8_BAR; PG8_WAIT_L(0); PG8_MMA(0, 0, At, B0); PG8_BAR; PG8_SCHED;
;             PG8_LDB(B1, 1, 1); PG8_STAGE(PG8_SB(1, 0), b3, voffB);
;             PG8_BAR; PG8_WAIT_L(0); PG8_MMA(0, 1, At, B1); PG8_BAR;
;             PG8_LDA(At, 1, 1); PG8_STAGE(PG8_SA(1, 0), a3, voffA);
;             PG8_BAR; PG8_WAIT_L(0); PG8_MMA(1, 0, At, B0); PG8_BAR; PG8_SCHED;
;             PG8_STAGE(PG8_SB(1, 1), b3 + hstepB, voffB);
;             PG8_WAIT_V(6); PG8_BAR; PG8_MMA(1, 1, At, B1); PG8_BAR;
	s_add_i32 s65, 0, 0x18000
	v_add_u32_e32 v226, s65, v169
	ds_read_b128 v[66:69], v226
	ds_read_b128 v[70:73], v226 offset:1024
	ds_read_b128 v[74:77], v226 offset:2048
	ds_read_b128 v[78:81], v226 offset:3072
	s_add_u32 s0, s26, 0x80000
	s_addc_u32 s1, s27, 0
	s_mov_b32 m0, s83
	v_lshl_add_u64 v[224:225], s[0:1], 0, v[166:167]
	ds_read_b128 v[90:93], v195 offset:32768
	ds_read_b128 v[94:97], v195 offset:33792
	ds_read_b128 v[98:101], v195 offset:34816
	ds_read_b128 v[102:105], v195 offset:35840
	ds_read_b128 v[176:179], v195 offset:36864
	ds_read_b128 v[180:183], v195 offset:37888
	ds_read_b128 v[184:187], v195 offset:38912
	ds_read_b128 v[188:191], v195 offset:39936
	global_load_lds_dwordx4 v[224:225], off
	v_lshl_add_u64 v[224:225], s[0:1], 0, v[164:165]
	s_mov_b32 m0, s50
	s_nop 0
	global_load_lds_dwordx4 v[224:225], off
	s_waitcnt lgkmcnt(11)
	s_add_i32 s26, 0, 0x1c000
	v_add_u32_e32 v226, s26, v169
	s_add_i32 s0, s65, s64
	ds_read_b128 v[196:199], v226
	ds_read_b128 v[200:203], v226 offset:1024
	ds_read_b128 v[204:207], v226 offset:2048
	ds_read_b128 v[220:223], v226 offset:3072
	s_waitcnt vmcnt(8) lgkmcnt(0)
	s_barrier
	v_mfma_f32_16x16x32_f16 v[158:161], v[66:69], v[90:93], v[158:161]
	v_mfma_f32_16x16x32_f16 v[158:161], v[70:73], v[94:97], v[158:161]
	v_mfma_f32_16x16x32_f16 v[154:157], v[74:77], v[90:93], v[154:157]
	v_mfma_f32_16x16x32_f16 v[154:157], v[78:81], v[94:97], v[154:157]
	v_mfma_f32_16x16x32_f16 v[142:145], v[66:69], v[98:101], v[142:145]
	v_mfma_f32_16x16x32_f16 v[134:137], v[74:77], v[98:101], v[134:137]
	v_mfma_f32_16x16x32_f16 v[126:129], v[66:69], v[176:179], v[126:129]
	v_mfma_f32_16x16x32_f16 v[118:121], v[74:77], v[176:179], v[118:121]
	v_mfma_f32_16x16x32_f16 v[110:113], v[66:69], v[184:187], v[110:113]
	v_mfma_f32_16x16x32_f16 v[106:109], v[74:77], v[184:187], v[106:109]
	v_mfma_f32_16x16x32_f16 v[142:145], v[70:73], v[102:105], v[142:145]
	v_mfma_f32_16x16x32_f16 v[134:137], v[78:81], v[102:105], v[134:137]
	v_mfma_f32_16x16x32_f16 v[126:129], v[70:73], v[180:183], v[126:129]
	v_mfma_f32_16x16x32_f16 v[118:121], v[78:81], v[180:183], v[118:121]
	v_mfma_f32_16x16x32_f16 v[110:113], v[70:73], v[188:191], v[110:113]
	v_mfma_f32_16x16x32_f16 v[106:109], v[78:81], v[188:191], v[106:109]
	v_mfma_f32_16x16x32_f16 v[146:149], v[204:207], v[90:93], v[146:149]
	v_mfma_f32_16x16x32_f16 v[150:153], v[196:199], v[90:93], v[150:153]
	v_mfma_f32_16x16x32_f16 v[146:149], v[220:223], v[94:97], v[146:149]
	v_mfma_f32_16x16x32_f16 v[138:141], v[196:199], v[98:101], v[138:141]
	v_mfma_f32_16x16x32_f16 v[150:153], v[200:203], v[94:97], v[150:153]
	v_mfma_f32_16x16x32_f16 v[138:141], v[200:203], v[102:105], v[138:141]
	v_mfma_f32_16x16x32_f16 v[130:133], v[204:207], v[98:101], v[130:133]
	v_mfma_f32_16x16x32_f16 v[130:133], v[220:223], v[102:105], v[130:133]
	v_mfma_f32_16x16x32_f16 v[122:125], v[196:199], v[176:179], v[122:125]
	v_mfma_f32_16x16x32_f16 v[122:125], v[200:203], v[180:183], v[122:125]
	v_mfma_f32_16x16x32_f16 v[114:117], v[204:207], v[176:179], v[114:117]
	v_mfma_f32_16x16x32_f16 v[86:89], v[196:199], v[184:187], v[86:89]
	v_mfma_f32_16x16x32_f16 v[82:85], v[204:207], v[184:187], v[82:85]
	v_mfma_f32_16x16x32_f16 v[114:117], v[220:223], v[180:183], v[114:117]
	v_mfma_f32_16x16x32_f16 v[86:89], v[200:203], v[188:191], v[86:89]
	v_mfma_f32_16x16x32_f16 v[82:85], v[220:223], v[188:191], v[82:85]
	s_barrier
	v_lshl_add_u64 v[224:225], v[192:193], 0, s[92:93]
	s_mov_b32 m0, s0
	s_nop 0
	global_load_lds_dwordx4 v[224:225], off
	v_lshl_add_u64 v[224:225], v[212:213], 0, s[92:93]
	s_add_i32 m0, s0, 0x2000
	s_nop 0
	global_load_lds_dwordx4 v[224:225], off
	s_mov_b32 m0, s89
	v_lshl_add_u64 v[192:193], v[214:215], 0, s[92:93]
	ds_read_b128 v[90:93], v195 offset:49152
	ds_read_b128 v[94:97], v195 offset:50176
	ds_read_b128 v[98:101], v195 offset:51200
	ds_read_b128 v[102:105], v195 offset:52224
	ds_read_b128 v[176:179], v195 offset:53248
	ds_read_b128 v[180:183], v195 offset:54272
	ds_read_b128 v[184:187], v195 offset:55296
	ds_read_b128 v[188:191], v195 offset:56320
	global_load_lds_dwordx4 v[192:193], off
	v_lshl_add_u64 v[192:193], v[216:217], 0, s[92:93]
	s_mov_b32 m0, s35
	s_nop 0
	global_load_lds_dwordx4 v[192:193], off
	s_add_u32 s0, s48, 0x80080
	s_addc_u32 s1, s49, 0
	s_add_i32 s26, s26, s64
	v_lshl_add_u64 v[224:225], s[0:1], 0, v[0:1]
	s_mov_b32 m0, s26
	s_nop 0
	global_load_lds_dwordx4 v[224:225], off
	v_lshl_add_u64 v[224:225], s[0:1], 0, v[162:163]
	s_add_i32 m0, s26, 0x2000
	s_nop 0
	global_load_lds_dwordx4 v[224:225], off
	s_add_i32 s60, s60, 2
	s_add_u32 vcc_lo, vcc_lo, 0x100
	s_addc_u32 vcc_hi, vcc_hi, 0
	s_add_u32 s21, s21, 0x100
	s_addc_u32 s66, s66, 0
	s_cmp_gt_u32 s60, 29
	s_waitcnt vmcnt(8) lgkmcnt(0)
	s_barrier
	v_mfma_f32_16x16x32_f16 v[62:65], v[66:69], v[90:93], v[62:65]
	v_mfma_f32_16x16x32_f16 v[58:61], v[74:77], v[90:93], v[58:61]
	v_mfma_f32_16x16x32_f16 v[46:49], v[66:69], v[98:101], v[46:49]
	v_mfma_f32_16x16x32_f16 v[38:41], v[74:77], v[98:101], v[38:41]
	v_mfma_f32_16x16x32_f16 v[30:33], v[66:69], v[176:179], v[30:33]
	v_mfma_f32_16x16x32_f16 v[22:25], v[74:77], v[176:179], v[22:25]
	v_mfma_f32_16x16x32_f16 v[14:17], v[66:69], v[184:187], v[14:17]
	v_mfma_f32_16x16x32_f16 v[10:13], v[74:77], v[184:187], v[10:13]
	v_mfma_f32_16x16x32_f16 v[62:65], v[70:73], v[94:97], v[62:65]
	v_mfma_f32_16x16x32_f16 v[58:61], v[78:81], v[94:97], v[58:61]
	v_mfma_f32_16x16x32_f16 v[46:49], v[70:73], v[102:105], v[46:49]
	v_mfma_f32_16x16x32_f16 v[38:41], v[78:81], v[102:105], v[38:41]
	v_mfma_f32_16x16x32_f16 v[30:33], v[70:73], v[180:183], v[30:33]
	v_mfma_f32_16x16x32_f16 v[22:25], v[78:81], v[180:183], v[22:25]
	v_mfma_f32_16x16x32_f16 v[14:17], v[70:73], v[188:191], v[14:17]
	v_mfma_f32_16x16x32_f16 v[10:13], v[78:81], v[188:191], v[10:13]
	v_mfma_f32_16x16x32_f16 v[54:57], v[196:199], v[90:93], v[54:57]
	v_mfma_f32_16x16x32_f16 v[50:53], v[204:207], v[90:93], v[50:53]
	v_mfma_f32_16x16x32_f16 v[42:45], v[196:199], v[98:101], v[42:45]
	v_mfma_f32_16x16x32_f16 v[34:37], v[204:207], v[98:101], v[34:37]
	v_mfma_f32_16x16x32_f16 v[26:29], v[196:199], v[176:179], v[26:29]
	v_mfma_f32_16x16x32_f16 v[18:21], v[204:207], v[176:179], v[18:21]
	v_mfma_f32_16x16x32_f16 v[6:9], v[196:199], v[184:187], v[6:9]
	v_mfma_f32_16x16x32_f16 v[2:5], v[204:207], v[184:187], v[2:5]
	v_mfma_f32_16x16x32_f16 v[54:57], v[200:203], v[94:97], v[54:57]
	v_mfma_f32_16x16x32_f16 v[50:53], v[220:223], v[94:97], v[50:53]
	v_mfma_f32_16x16x32_f16 v[42:45], v[200:203], v[102:105], v[42:45]
	v_mfma_f32_16x16x32_f16 v[34:37], v[220:223], v[102:105], v[34:37]
	v_mfma_f32_16x16x32_f16 v[26:29], v[200:203], v[180:183], v[26:29]
	v_mfma_f32_16x16x32_f16 v[18:21], v[220:223], v[180:183], v[18:21]
	v_mfma_f32_16x16x32_f16 v[6:9], v[200:203], v[188:191], v[6:9]
	v_mfma_f32_16x16x32_f16 v[2:5], v[220:223], v[188:191], v[2:5]
	s_barrier
	s_cbranch_scc1 .Lg4x_92

; #define PG8_STAGE(bufoff, gbase, voff) do { _Pragma("unroll") for (int _i = 0; _i < 2; ++_i) \
;         __builtin_amdgcn_global_load_lds((const unsigned*)((const char*)(gbase) + (voff)[_i]), (LAS unsigned*)(lds + (bufoff) + ldsw + _i * 8192), 16, 0, 0); } while (0)
; #define PG8_LDA(dst, b, h) do { _Pragma("unroll") for (int m = 0; m < 4; ++m) _Pragma("unroll") for (int k = 0; k < 2; ++k) dst[m][k] = *(const LAS h16x8*)(lds + PG8_SA(b, h) + aoff + m * 2048 + k * 1024); } while (0)
; #define PG8_LDB(dst, b, h) do { _Pragma("unroll") for (int n = 0; n < 2; ++n) _Pragma("unroll") for (int k = 0; k < 2; ++k) dst[n][k] = *(const LAS h16x8*)(lds + PG8_SB(b, h) + boff + n * 2048 + k * 1024); } while (0)
; #define PG8_MMA(ai, bj, At, Bt_) do { __builtin_amdgcn_s_setprio(1); _Pragma("unroll") for (int m = 0; m < 4; ++m) _Pragma("unroll") for (int n = 0; n < 2; ++n) _Pragma("unroll") for (int k = 0; k < 2; ++k) \
;         acc[ai][bj][m][n] = __builtin_amdgcn_mfma_f32_16x16x32_f16(Bt_[n][k], At[m][k], acc[ai][bj][m][n], 0, 0, 0); __builtin_amdgcn_s_setprio(0); } while (0)
; #define PG8_WAIT_V(n) asm volatile("s_waitcnt vmcnt(" #n ")" ::: "memory")
; #define PG8_WAIT_L(n) asm volatile("s_waitcnt lgkmcnt(" #n ")" ::: "memory")
; #define PG8_BAR __builtin_amdgcn_s_barrier()
; #define PG8_SCHED __builtin_amdgcn_sched_barrier(0)
; template <class Epi, class AMap>
; __device__ __forceinline__ void gemm_phase(LAS unsigned char* lds, const AMap am, const int lda, const h16* Bt, const int ldb, const int M, const int N, const int K, const Epi& E) {
;     ...
;             PG8_LDB(B0, 0, 0); PG8_SCHED; PG8_LDA(At, 0, 0); PG8_STAGE(PG8_SA(1, 1), a1 + hstepA, voffA);
;             PG8_WAIT_L(8); PG8_BAR; PG8_WAIT_L(0); PG8_MMA(0, 0, At, B0); PG8_BAR; PG8_SCHED;
;             PG8_LDB(B1, 0, 1); PG8_STAGE(PG8_SB(0, 0), b2, voffB);
;             PG8_BAR; PG8_WAIT_L(0); PG8_MMA(0, 1, At, B1); PG8_BAR;
;             PG8_LDA(At, 0, 1); PG8_STAGE(PG8_SA(0, 0), a2, voffA);
;             PG8_BAR; PG8_WAIT_L(0); PG8_MMA(1, 0, At, B0); PG8_BAR; PG8_SCHED;
;             PG8_STAGE(PG8_SB(0, 1), b2 + hstepB, voffB);
;             PG8_WAIT_V(6); PG8_BAR; PG8_MMA(1, 1, At, B1); PG8_BAR;
.Lgy2:
.Lg4p_147:
	s_add_u32 s46, s26, 0xfff80080
	s_addc_u32 s47, s27, -1
	s_add_i32 s60, 0, 0x10000
	v_add_u32_e32 v144, s60, v147
	ds_read_b128 v[140:143], v144
	ds_read_b128 v[150:153], v144 offset:1024
	ds_read_b128 v[154:157], v144 offset:2048
	ds_read_b128 v[158:161], v144 offset:3072
	s_cmp_eq_u32 s51, 28
	s_cselect_b32 s49, s41, s47
	s_cselect_b32 s48, s29, s46
	s_cselect_b32 s47, s1, s50
	s_cselect_b32 s46, s20, s21
	v_lshl_add_u64 v[144:145], s[26:27], 0, v[136:137]
	s_add_i32 m0, s23, 0xc000
	ds_read_b128 v[162:165], v149
	ds_read_b128 v[166:169], v149 offset:1024
	ds_read_b128 v[170:173], v149 offset:2048
	ds_read_b128 v[174:177], v149 offset:3072
	ds_read_b128 v[178:181], v149 offset:4096
	ds_read_b128 v[182:185], v149 offset:5120
	ds_read_b128 v[186:189], v149 offset:6144
	ds_read_b128 v[190:193], v149 offset:7168
	global_load_lds_dwordx4 v[144:145], off
	v_lshl_add_u64 v[144:145], s[26:27], 0, v[138:139]
	s_add_i32 m0, s23, 0xe000
	s_nop 0
	global_load_lds_dwordx4 v[144:145], off
	s_waitcnt lgkmcnt(11)
	s_add_i32 s66, 0, 0x14000
	v_add_u32_e32 v144, s66, v147
	s_add_i32 s60, s60, s64
	ds_read_b128 v[194:197], v144
	ds_read_b128 v[198:201], v144 offset:1024
	ds_read_b128 v[202:205], v144 offset:2048
	ds_read_b128 v[220:223], v144 offset:3072
	s_waitcnt vmcnt(40) lgkmcnt(0)
	s_barrier
	v_mfma_f32_16x16x32_f16 v[126:129], v[140:143], v[162:165], 0
	v_mfma_f32_16x16x32_f16 v[122:125], v[154:157], v[162:165], 0
	v_mfma_f32_16x16x32_f16 v[110:113], v[140:143], v[170:173], 0
	v_mfma_f32_16x16x32_f16 v[106:109], v[154:157], v[170:173], 0
	v_mfma_f32_16x16x32_f16 v[94:97], v[140:143], v[178:181], 0
	v_mfma_f32_16x16x32_f16 v[90:93], v[154:157], v[178:181], 0
	v_mfma_f32_16x16x32_f16 v[78:81], v[140:143], v[186:189], 0
	v_mfma_f32_16x16x32_f16 v[74:77], v[154:157], v[186:189], 0
	v_mfma_f32_16x16x32_f16 v[126:129], v[150:153], v[166:169], v[126:129]
	v_mfma_f32_16x16x32_f16 v[122:125], v[158:161], v[166:169], v[122:125]
	v_mfma_f32_16x16x32_f16 v[110:113], v[150:153], v[174:177], v[110:113]
	v_mfma_f32_16x16x32_f16 v[106:109], v[158:161], v[174:177], v[106:109]
	v_mfma_f32_16x16x32_f16 v[94:97], v[150:153], v[182:185], v[94:97]
	v_mfma_f32_16x16x32_f16 v[90:93], v[158:161], v[182:185], v[90:93]
	v_mfma_f32_16x16x32_f16 v[78:81], v[150:153], v[190:193], v[78:81]
	v_mfma_f32_16x16x32_f16 v[74:77], v[158:161], v[190:193], v[74:77]
	v_mfma_f32_16x16x32_f16 v[118:121], v[194:197], v[162:165], 0
	v_mfma_f32_16x16x32_f16 v[114:117], v[202:205], v[162:165], 0
	v_mfma_f32_16x16x32_f16 v[102:105], v[194:197], v[170:173], 0
	v_mfma_f32_16x16x32_f16 v[98:101], v[202:205], v[170:173], 0
	v_mfma_f32_16x16x32_f16 v[86:89], v[194:197], v[178:181], 0
	v_mfma_f32_16x16x32_f16 v[82:85], v[202:205], v[178:181], 0
	v_mfma_f32_16x16x32_f16 v[70:73], v[194:197], v[186:189], 0
	v_mfma_f32_16x16x32_f16 v[66:69], v[202:205], v[186:189], 0
	v_mfma_f32_16x16x32_f16 v[118:121], v[198:201], v[166:169], v[118:121]
	v_mfma_f32_16x16x32_f16 v[114:117], v[220:223], v[166:169], v[114:117]
	v_mfma_f32_16x16x32_f16 v[102:105], v[198:201], v[174:177], v[102:105]
	v_mfma_f32_16x16x32_f16 v[98:101], v[220:223], v[174:177], v[98:101]
	v_mfma_f32_16x16x32_f16 v[86:89], v[198:201], v[182:185], v[86:89]
	v_mfma_f32_16x16x32_f16 v[82:85], v[220:223], v[182:185], v[82:85]
	v_mfma_f32_16x16x32_f16 v[70:73], v[198:201], v[190:193], v[70:73]
	v_mfma_f32_16x16x32_f16 v[66:69], v[220:223], v[190:193], v[66:69]
	s_barrier
	v_lshl_add_u64 v[144:145], s[46:47], 0, v[0:1]
	s_mov_b32 m0, s60
	v_lshl_add_u64 v[206:207], s[46:47], 0, v[134:135]
	global_load_lds_dwordx4 v[144:145], off
	s_add_i32 m0, s60, 0x2000
	s_nop 0
	global_load_lds_dwordx4 v[206:207], off
	s_mov_b32 m0, s23
	v_lshl_add_u64 v[212:213], s[48:49], 0, v[130:131]
	ds_read_b128 v[162:165], v149 offset:16384
	ds_read_b128 v[166:169], v149 offset:17408
	ds_read_b128 v[170:173], v149 offset:18432
	ds_read_b128 v[174:177], v149 offset:19456
	ds_read_b128 v[178:181], v149 offset:20480
	ds_read_b128 v[182:185], v149 offset:21504
	ds_read_b128 v[186:189], v149 offset:22528
	ds_read_b128 v[190:193], v149 offset:23552
	global_load_lds_dwordx4 v[212:213], off
	v_lshl_add_u64 v[214:215], s[48:49], 0, v[132:133]
	s_mov_b32 m0, s71
	s_nop 0
	global_load_lds_dwordx4 v[214:215], off
	s_add_u32 s78, s46, 0x80000
	s_addc_u32 s79, s47, 0
	s_add_i32 s60, s66, s64
	v_lshl_add_u64 v[232:233], s[78:79], 0, v[0:1]
	s_mov_b32 m0, s60
	s_nop 0
	global_load_lds_dwordx4 v[232:233], off
	v_lshl_add_u64 v[232:233], s[78:79], 0, v[134:135]
	s_add_i32 m0, s60, 0x2000
	s_nop 0
	global_load_lds_dwordx4 v[232:233], off
	s_waitcnt vmcnt(8) lgkmcnt(0)
	s_barrier
; #define PG8_STAGE(bufoff, gbase, voff) do { _Pragma("unroll") for (int _i = 0; _i < 2; ++_i) \
;         __builtin_amdgcn_global_load_lds((const unsigned*)((const char*)(gbase) + (voff)[_i]), (LAS unsigned*)(lds + (bufoff) + ldsw + _i * 8192), 16, 0, 0); } while (0)
; #define PG8_LDA(dst, b, h) do { _Pragma("unroll") for (int m = 0; m < 4; ++m) _Pragma("unroll") for (int k = 0; k < 2; ++k) dst[m][k] = *(const LAS h16x8*)(lds + PG8_SA(b, h) + aoff + m * 2048 + k * 1024); } while (0)
; #define PG8_LDB(dst, b, h) do { _Pragma("unroll") for (int n = 0; n < 2; ++n) _Pragma("unroll") for (int k = 0; k < 2; ++k) dst[n][k] = *(const LAS h16x8*)(lds + PG8_SB(b, h) + boff + n * 2048 + k * 1024); } while (0)
; #define PG8_MMA(ai, bj, At, Bt_) do { __builtin_amdgcn_s_setprio(1); _Pragma("unroll") for (int m = 0; m < 4; ++m) _Pragma("unroll") for (int n = 0; n < 2; ++n) _Pragma("unroll") for (int k = 0; k < 2; ++k) \
;         acc[ai][bj][m][n] = __builtin_amdgcn_mfma_f32_16x16x32_f16(Bt_[n][k], At[m][k], acc[ai][bj][m][n], 0, 0, 0); __builtin_amdgcn_s_setprio(0); } while (0)
; #define PG8_WAIT_V(n) asm volatile("s_waitcnt vmcnt(" #n ")" ::: "memory")
; #define PG8_WAIT_L(n) asm volatile("s_waitcnt lgkmcnt(" #n ")" ::: "memory")
; #define PG8_BAR __builtin_amdgcn_s_barrier()
; #define PG8_SCHED __builtin_amdgcn_sched_barrier(0)
; template <class Epi, class AMap>
; __device__ __forceinline__ void gemm_phase(LAS unsigned char* lds, const AMap am, const int lda, const h16* Bt, const int ldb, const int M, const int N, const int K, const Epi& E) {
;     ...
;             PG8_BAR; PG8_WAIT_L(0); PG8_MMA(1, 0, At, B0); PG8_BAR; PG8_SCHED;
;             PG8_STAGE(PG8_SB(0, 1), b2 + hstepB, voffB);
;             PG8_WAIT_V(6); PG8_BAR; PG8_MMA(1, 1, At, B1); PG8_BAR;
;             PG8_LDB(B0, 1, 0); PG8_SCHED; PG8_LDA(At, 1, 0); PG8_STAGE(PG8_SA(0, 1), a2 + hstepA, voffA);
;             PG8_WAIT_L(8); PG8_BAR; PG8_WAIT_L(0); PG8_MMA(0, 0, At, B0); PG8_BAR; PG8_SCHED;
;             PG8_LDB(B1, 1, 1); PG8_STAGE(PG8_SB(1, 0), b3, voffB);
;             PG8_BAR; PG8_WAIT_L(0); PG8_MMA(0, 1, At, B1); PG8_BAR;
;             PG8_LDA(At, 1, 1); PG8_STAGE(PG8_SA(1, 0), a3, voffA);
	v_mfma_f32_16x16x32_f16 v[62:65], v[140:143], v[162:165], 0
	v_mfma_f32_16x16x32_f16 v[58:61], v[154:157], v[162:165], 0
	v_mfma_f32_16x16x32_f16 v[46:49], v[140:143], v[170:173], 0
	v_mfma_f32_16x16x32_f16 v[42:45], v[154:157], v[170:173], 0
	v_mfma_f32_16x16x32_f16 v[30:33], v[140:143], v[178:181], 0
	v_mfma_f32_16x16x32_f16 v[26:29], v[154:157], v[178:181], 0
	v_mfma_f32_16x16x32_f16 v[14:17], v[140:143], v[186:189], 0
	v_mfma_f32_16x16x32_f16 v[10:13], v[154:157], v[186:189], 0
	v_mfma_f32_16x16x32_f16 v[62:65], v[150:153], v[166:169], v[62:65]
	v_mfma_f32_16x16x32_f16 v[58:61], v[158:161], v[166:169], v[58:61]
	v_mfma_f32_16x16x32_f16 v[46:49], v[150:153], v[174:177], v[46:49]
	v_mfma_f32_16x16x32_f16 v[42:45], v[158:161], v[174:177], v[42:45]
	v_mfma_f32_16x16x32_f16 v[30:33], v[150:153], v[182:185], v[30:33]
	v_mfma_f32_16x16x32_f16 v[26:29], v[158:161], v[182:185], v[26:29]
	v_mfma_f32_16x16x32_f16 v[14:17], v[150:153], v[190:193], v[14:17]
	v_mfma_f32_16x16x32_f16 v[10:13], v[158:161], v[190:193], v[10:13]
	v_mfma_f32_16x16x32_f16 v[54:57], v[194:197], v[162:165], 0
	v_mfma_f32_16x16x32_f16 v[50:53], v[202:205], v[162:165], 0
	v_mfma_f32_16x16x32_f16 v[38:41], v[194:197], v[170:173], 0
	v_mfma_f32_16x16x32_f16 v[34:37], v[202:205], v[170:173], 0
	v_mfma_f32_16x16x32_f16 v[22:25], v[194:197], v[178:181], 0
	v_mfma_f32_16x16x32_f16 v[18:21], v[202:205], v[178:181], 0
	v_mfma_f32_16x16x32_f16 v[6:9], v[194:197], v[186:189], 0
	v_mfma_f32_16x16x32_f16 v[2:5], v[202:205], v[186:189], 0
	v_mfma_f32_16x16x32_f16 v[54:57], v[198:201], v[166:169], v[54:57]
	v_mfma_f32_16x16x32_f16 v[50:53], v[220:223], v[166:169], v[50:53]
	v_mfma_f32_16x16x32_f16 v[38:41], v[198:201], v[174:177], v[38:41]
	v_mfma_f32_16x16x32_f16 v[34:37], v[220:223], v[174:177], v[34:37]
	v_mfma_f32_16x16x32_f16 v[22:25], v[198:201], v[182:185], v[22:25]
	v_mfma_f32_16x16x32_f16 v[18:21], v[220:223], v[182:185], v[18:21]
	v_mfma_f32_16x16x32_f16 v[6:9], v[198:201], v[190:193], v[6:9]
	v_mfma_f32_16x16x32_f16 v[2:5], v[220:223], v[190:193], v[2:5]
	s_barrier
	s_add_i32 s60, 0, 0x18000
	v_add_u32_e32 v234, s60, v147
	ds_read_b128 v[140:143], v234
	ds_read_b128 v[150:153], v234 offset:1024
	ds_read_b128 v[154:157], v234 offset:2048
	ds_read_b128 v[158:161], v234 offset:3072
	s_add_u32 s48, s48, 0x80000
	s_addc_u32 s49, s49, 0
	s_mov_b32 m0, s72
	v_lshl_add_u64 v[232:233], s[48:49], 0, v[130:131]
	ds_read_b128 v[162:165], v149 offset:32768
	ds_read_b128 v[166:169], v149 offset:33792
	ds_read_b128 v[170:173], v149 offset:34816
	ds_read_b128 v[174:177], v149 offset:35840
	ds_read_b128 v[178:181], v149 offset:36864
	ds_read_b128 v[182:185], v149 offset:37888
	ds_read_b128 v[186:189], v149 offset:38912
	ds_read_b128 v[190:193], v149 offset:39936
	global_load_lds_dwordx4 v[232:233], off
	v_lshl_add_u64 v[232:233], s[48:49], 0, v[132:133]
	s_mov_b32 m0, s73
	s_nop 0
	global_load_lds_dwordx4 v[232:233], off
	s_waitcnt lgkmcnt(11)
	s_add_i32 s48, 0, 0x1c000
	s_add_i32 s49, s60, s64
	v_add_u32_e32 v216, s48, v147
	v_lshl_add_u64 v[144:145], v[144:145], 0, s[92:93]
	s_mov_b32 m0, s49
	ds_read_b128 v[194:197], v216
	ds_read_b128 v[198:201], v216 offset:1024
	ds_read_b128 v[202:205], v216 offset:2048
	ds_read_b128 v[220:223], v216 offset:3072
	s_waitcnt vmcnt(8) lgkmcnt(0)
	s_barrier
	v_mfma_f32_16x16x32_f16 v[126:129], v[140:143], v[162:165], v[126:129]
	v_mfma_f32_16x16x32_f16 v[122:125], v[154:157], v[162:165], v[122:125]
	v_mfma_f32_16x16x32_f16 v[110:113], v[140:143], v[170:173], v[110:113]
	v_mfma_f32_16x16x32_f16 v[106:109], v[154:157], v[170:173], v[106:109]
	v_mfma_f32_16x16x32_f16 v[94:97], v[140:143], v[178:181], v[94:97]
	v_mfma_f32_16x16x32_f16 v[90:93], v[154:157], v[178:181], v[90:93]
	v_mfma_f32_16x16x32_f16 v[78:81], v[140:143], v[186:189], v[78:81]
	v_mfma_f32_16x16x32_f16 v[74:77], v[154:157], v[186:189], v[74:77]
	v_mfma_f32_16x16x32_f16 v[126:129], v[150:153], v[166:169], v[126:129]
	v_mfma_f32_16x16x32_f16 v[122:125], v[158:161], v[166:169], v[122:125]
	v_mfma_f32_16x16x32_f16 v[110:113], v[150:153], v[174:177], v[110:113]
	v_mfma_f32_16x16x32_f16 v[106:109], v[158:161], v[174:177], v[106:109]
	v_mfma_f32_16x16x32_f16 v[94:97], v[150:153], v[182:185], v[94:97]
	v_mfma_f32_16x16x32_f16 v[90:93], v[158:161], v[182:185], v[90:93]
	v_mfma_f32_16x16x32_f16 v[78:81], v[150:153], v[190:193], v[78:81]
	v_mfma_f32_16x16x32_f16 v[74:77], v[158:161], v[190:193], v[74:77]
	v_mfma_f32_16x16x32_f16 v[118:121], v[194:197], v[162:165], v[118:121]
	v_mfma_f32_16x16x32_f16 v[114:117], v[202:205], v[162:165], v[114:117]
	v_mfma_f32_16x16x32_f16 v[102:105], v[194:197], v[170:173], v[102:105]
	v_mfma_f32_16x16x32_f16 v[98:101], v[202:205], v[170:173], v[98:101]
	v_mfma_f32_16x16x32_f16 v[86:89], v[194:197], v[178:181], v[86:89]
	v_mfma_f32_16x16x32_f16 v[82:85], v[202:205], v[178:181], v[82:85]
	v_mfma_f32_16x16x32_f16 v[70:73], v[194:197], v[186:189], v[70:73]
	v_mfma_f32_16x16x32_f16 v[66:69], v[202:205], v[186:189], v[66:69]
	v_mfma_f32_16x16x32_f16 v[118:121], v[198:201], v[166:169], v[118:121]
	v_mfma_f32_16x16x32_f16 v[114:117], v[220:223], v[166:169], v[114:117]
	v_mfma_f32_16x16x32_f16 v[102:105], v[198:201], v[174:177], v[102:105]
	v_mfma_f32_16x16x32_f16 v[98:101], v[220:223], v[174:177], v[98:101]
	v_mfma_f32_16x16x32_f16 v[86:89], v[198:201], v[182:185], v[86:89]
	v_mfma_f32_16x16x32_f16 v[82:85], v[220:223], v[182:185], v[82:85]
	v_mfma_f32_16x16x32_f16 v[70:73], v[198:201], v[190:193], v[70:73]
	v_mfma_f32_16x16x32_f16 v[66:69], v[220:223], v[190:193], v[66:69]
	s_barrier
; #define PG8_STAGE(bufoff, gbase, voff) do { _Pragma("unroll") for (int _i = 0; _i < 2; ++_i) \
;         __builtin_amdgcn_global_load_lds((const unsigned*)((const char*)(gbase) + (voff)[_i]), (LAS unsigned*)(lds + (bufoff) + ldsw + _i * 8192), 16, 0, 0); } while (0)
; #define PG8_LDA(dst, b, h) do { _Pragma("unroll") for (int m = 0; m < 4; ++m) _Pragma("unroll") for (int k = 0; k < 2; ++k) dst[m][k] = *(const LAS h16x8*)(lds + PG8_SA(b, h) + aoff + m * 2048 + k * 1024); } while (0)
; #define PG8_LDB(dst, b, h) do { _Pragma("unroll") for (int n = 0; n < 2; ++n) _Pragma("unroll") for (int k = 0; k < 2; ++k) dst[n][k] = *(const LAS h16x8*)(lds + PG8_SB(b, h) + boff + n * 2048 + k * 1024); } while (0)
; #define PG8_MMA(ai, bj, At, Bt_) do { __builtin_amdgcn_s_setprio(1); _Pragma("unroll") for (int m = 0; m < 4; ++m) _Pragma("unroll") for (int n = 0; n < 2; ++n) _Pragma("unroll") for (int k = 0; k < 2; ++k) \
;         acc[ai][bj][m][n] = __builtin_amdgcn_mfma_f32_16x16x32_f16(Bt_[n][k], At[m][k], acc[ai][bj][m][n], 0, 0, 0); __builtin_amdgcn_s_setprio(0); } while (0)
; #define PG8_WAIT_V(n) asm volatile("s_waitcnt vmcnt(" #n ")" ::: "memory")
; #define PG8_WAIT_L(n) asm volatile("s_waitcnt lgkmcnt(" #n ")" ::: "memory")
; #define PG8_BAR __builtin_amdgcn_s_barrier()
; #define PG8_SCHED __builtin_amdgcn_sched_barrier(0)
; template <class Epi, class AMap>
; __device__ __forceinline__ void gemm_phase(LAS unsigned char* lds, const AMap am, const int lda, const h16* Bt, const int ldb, const int M, const int N, const int K, const Epi& E) {
;     ...
;             PG8_LDB(B1, 1, 1); PG8_STAGE(PG8_SB(1, 0), b3, voffB);
;             PG8_BAR; PG8_WAIT_L(0); PG8_MMA(0, 1, At, B1); PG8_BAR;
;             PG8_LDA(At, 1, 1); PG8_STAGE(PG8_SA(1, 0), a3, voffA);
;             PG8_BAR; PG8_WAIT_L(0); PG8_MMA(1, 0, At, B0); PG8_BAR; PG8_SCHED;
;             PG8_STAGE(PG8_SB(1, 1), b3 + hstepB, voffB);
;             PG8_WAIT_V(6); PG8_BAR; PG8_MMA(1, 1, At, B1); PG8_BAR;
;         }
	global_load_lds_dwordx4 v[144:145], off
	v_lshl_add_u64 v[144:145], v[206:207], 0, s[92:93]
	s_add_i32 m0, s49, 0x2000
	s_nop 0
	global_load_lds_dwordx4 v[144:145], off
	s_mov_b32 m0, s74
	v_lshl_add_u64 v[144:145], v[212:213], 0, s[92:93]
	ds_read_b128 v[162:165], v149 offset:49152
	ds_read_b128 v[166:169], v149 offset:50176
	ds_read_b128 v[170:173], v149 offset:51200
	ds_read_b128 v[174:177], v149 offset:52224
	ds_read_b128 v[178:181], v149 offset:53248
	ds_read_b128 v[182:185], v149 offset:54272
	ds_read_b128 v[186:189], v149 offset:55296
	ds_read_b128 v[190:193], v149 offset:56320
	global_load_lds_dwordx4 v[144:145], off
	v_lshl_add_u64 v[144:145], v[214:215], 0, s[92:93]
	s_mov_b32 m0, s75
	s_nop 0
	global_load_lds_dwordx4 v[144:145], off
	s_add_u32 s46, s46, 0x80080
	s_addc_u32 s47, s47, 0
	s_add_i32 s48, s48, s64
	v_lshl_add_u64 v[232:233], s[46:47], 0, v[0:1]
	s_mov_b32 m0, s48
	s_nop 0
	global_load_lds_dwordx4 v[232:233], off
	v_lshl_add_u64 v[232:233], s[46:47], 0, v[134:135]
	s_add_i32 m0, s48, 0x2000
	s_nop 0
	global_load_lds_dwordx4 v[232:233], off
	s_add_i32 s51, s51, 2
	s_add_u32 s26, s26, 0x100
	s_addc_u32 s27, s27, 0
	s_add_u32 s21, s21, 0x100
	s_addc_u32 s50, s50, 0
	s_cmp_gt_u32 s51, 29
	s_waitcnt vmcnt(8) lgkmcnt(0)
	s_barrier
	v_mfma_f32_16x16x32_f16 v[62:65], v[140:143], v[162:165], v[62:65]
	v_mfma_f32_16x16x32_f16 v[58:61], v[154:157], v[162:165], v[58:61]
	v_mfma_f32_16x16x32_f16 v[46:49], v[140:143], v[170:173], v[46:49]
	v_mfma_f32_16x16x32_f16 v[42:45], v[154:157], v[170:173], v[42:45]
	v_mfma_f32_16x16x32_f16 v[30:33], v[140:143], v[178:181], v[30:33]
	v_mfma_f32_16x16x32_f16 v[26:29], v[154:157], v[178:181], v[26:29]
	v_mfma_f32_16x16x32_f16 v[14:17], v[140:143], v[186:189], v[14:17]
	v_mfma_f32_16x16x32_f16 v[10:13], v[154:157], v[186:189], v[10:13]
	v_mfma_f32_16x16x32_f16 v[62:65], v[150:153], v[166:169], v[62:65]
	v_mfma_f32_16x16x32_f16 v[58:61], v[158:161], v[166:169], v[58:61]
	v_mfma_f32_16x16x32_f16 v[46:49], v[150:153], v[174:177], v[46:49]
	v_mfma_f32_16x16x32_f16 v[42:45], v[158:161], v[174:177], v[42:45]
	v_mfma_f32_16x16x32_f16 v[30:33], v[150:153], v[182:185], v[30:33]
	v_mfma_f32_16x16x32_f16 v[26:29], v[158:161], v[182:185], v[26:29]
	v_mfma_f32_16x16x32_f16 v[14:17], v[150:153], v[190:193], v[14:17]
	v_mfma_f32_16x16x32_f16 v[10:13], v[158:161], v[190:193], v[10:13]
	v_mfma_f32_16x16x32_f16 v[54:57], v[194:197], v[162:165], v[54:57]
	v_mfma_f32_16x16x32_f16 v[50:53], v[202:205], v[162:165], v[50:53]
	v_mfma_f32_16x16x32_f16 v[38:41], v[194:197], v[170:173], v[38:41]
	v_mfma_f32_16x16x32_f16 v[34:37], v[202:205], v[170:173], v[34:37]
	v_mfma_f32_16x16x32_f16 v[22:25], v[194:197], v[178:181], v[22:25]
	v_mfma_f32_16x16x32_f16 v[18:21], v[202:205], v[178:181], v[18:21]
	v_mfma_f32_16x16x32_f16 v[6:9], v[194:197], v[186:189], v[6:9]
	v_mfma_f32_16x16x32_f16 v[2:5], v[202:205], v[186:189], v[2:5]
	v_mfma_f32_16x16x32_f16 v[54:57], v[198:201], v[166:169], v[54:57]
	v_mfma_f32_16x16x32_f16 v[50:53], v[220:223], v[166:169], v[50:53]
	v_mfma_f32_16x16x32_f16 v[38:41], v[198:201], v[174:177], v[38:41]
	v_mfma_f32_16x16x32_f16 v[34:37], v[220:223], v[174:177], v[34:37]
	v_mfma_f32_16x16x32_f16 v[22:25], v[198:201], v[182:185], v[22:25]
	v_mfma_f32_16x16x32_f16 v[18:21], v[220:223], v[182:185], v[18:21]
	v_mfma_f32_16x16x32_f16 v[6:9], v[198:201], v[190:193], v[6:9]
	v_mfma_f32_16x16x32_f16 v[2:5], v[220:223], v[190:193], v[2:5]
	s_barrier
	s_cbranch_scc1 .Lg4x_147

; #define PG8_STAGE(bufoff, gbase, voff) do { _Pragma("unroll") for (int _i = 0; _i < 2; ++_i) \
;         __builtin_amdgcn_global_load_lds((const unsigned*)((const char*)(gbase) + (voff)[_i]), (LAS unsigned*)(lds + (bufoff) + ldsw + _i * 8192), 16, 0, 0); } while (0)
; #define PG8_LDA(dst, b, h) do { _Pragma("unroll") for (int m = 0; m < 4; ++m) _Pragma("unroll") for (int k = 0; k < 2; ++k) dst[m][k] = *(const LAS h16x8*)(lds + PG8_SA(b, h) + aoff + m * 2048 + k * 1024); } while (0)
; #define PG8_LDB(dst, b, h) do { _Pragma("unroll") for (int n = 0; n < 2; ++n) _Pragma("unroll") for (int k = 0; k < 2; ++k) dst[n][k] = *(const LAS h16x8*)(lds + PG8_SB(b, h) + boff + n * 2048 + k * 1024); } while (0)
; #define PG8_MMA(ai, bj, At, Bt_) do { __builtin_amdgcn_s_setprio(1); _Pragma("unroll") for (int m = 0; m < 4; ++m) _Pragma("unroll") for (int n = 0; n < 2; ++n) _Pragma("unroll") for (int k = 0; k < 2; ++k) \
;         acc[ai][bj][m][n] = __builtin_amdgcn_mfma_f32_16x16x32_f16(Bt_[n][k], At[m][k], acc[ai][bj][m][n], 0, 0, 0); __builtin_amdgcn_s_setprio(0); } while (0)
; #define PG8_WAIT_V(n) asm volatile("s_waitcnt vmcnt(" #n ")" ::: "memory")
; #define PG8_WAIT_L(n) asm volatile("s_waitcnt lgkmcnt(" #n ")" ::: "memory")
; template <class Epi, class AMap>
; __device__ __forceinline__ void gemm_phase(LAS unsigned char* lds, const AMap am, const int lda, const h16* Bt, const int ldb, const int M, const int N, const int K, const Epi& E) {
;     ...
;             const bool last = (t == nt - 2);
;             const char* a1 = cA + (size_t)(t + 1) * kstep;
;             const char* a2 = last ? nA : cA + (size_t)(t + 2) * kstep; const char* b2 = last ? nB : cB + (size_t)(t + 2) * kstep;
;             const char* a3 = a2 + kstep; const char* b3 = b2 + kstep;
;             PG8_LDB(B0, 0, 0); PG8_SCHED; PG8_LDA(At, 0, 0); PG8_STAGE(PG8_SA(1, 1), a1 + hstepA, voffA);
;             PG8_WAIT_L(8); PG8_BAR; PG8_WAIT_L(0); PG8_MMA(0, 0, At, B0); PG8_BAR; PG8_SCHED;
;             PG8_LDB(B1, 0, 1); PG8_STAGE(PG8_SB(0, 0), b2, voffB);
;             PG8_BAR; PG8_WAIT_L(0); PG8_MMA(0, 1, At, B1); PG8_BAR;
;             PG8_LDA(At, 0, 1); PG8_STAGE(PG8_SA(0, 0), a2, voffA);
;             PG8_BAR; PG8_WAIT_L(0); PG8_MMA(1, 0, At, B0); PG8_BAR; PG8_SCHED;
;             PG8_STAGE(PG8_SB(0, 1), b2 + hstepB, voffB);
;             PG8_WAIT_V(6); PG8_BAR; PG8_MMA(1, 1, At, B1); PG8_BAR;
.Lgy8:
.Lg4p_799:
	s_add_u32 s40, s0, 0xfff80080
	s_addc_u32 s41, s1, -1
	s_add_i32 s45, 0, 0x10000
	v_add_u32_e32 v152, s45, v155
	ds_read_b128 v[130:133], v152
	ds_read_b128 v[134:137], v152 offset:1024
	ds_read_b128 v[148:151], v152 offset:2048
	ds_read_b128 v[158:161], v152 offset:3072
	s_cmp_eq_u32 s43, 28
	s_cselect_b32 s49, s47, s41
	s_cselect_b32 s48, s46, s40
	s_cselect_b32 s41, s29, s35
	s_cselect_b32 s40, s20, s21
	v_lshl_add_u64 v[152:153], s[0:1], 0, v[144:145]
	s_add_i32 m0, s23, 0xc000
	ds_read_b128 v[162:165], v157
	ds_read_b128 v[166:169], v157 offset:1024
	ds_read_b128 v[170:173], v157 offset:2048
	ds_read_b128 v[174:177], v157 offset:3072
	ds_read_b128 v[178:181], v157 offset:4096
	ds_read_b128 v[182:185], v157 offset:5120
	ds_read_b128 v[186:189], v157 offset:6144
	ds_read_b128 v[190:193], v157 offset:7168
	global_load_lds_dwordx4 v[152:153], off
	v_lshl_add_u64 v[152:153], s[0:1], 0, v[146:147]
	s_add_i32 m0, s23, 0xe000
	s_nop 0
	global_load_lds_dwordx4 v[152:153], off
	s_waitcnt lgkmcnt(11)
	s_add_i32 s60, 0, 0x14000
	v_add_u32_e32 v152, s60, v155
	s_add_i32 s45, s45, s72
	ds_read_b128 v[194:197], v152
	ds_read_b128 v[198:201], v152 offset:1024
	ds_read_b128 v[202:205], v152 offset:2048
	ds_read_b128 v[220:223], v152 offset:3072
	s_waitcnt vmcnt(24) lgkmcnt(0)
	s_barrier
	v_mfma_f32_16x16x32_f16 v[126:129], v[130:133], v[162:165], 0
	v_mfma_f32_16x16x32_f16 v[122:125], v[148:151], v[162:165], 0
	v_mfma_f32_16x16x32_f16 v[110:113], v[130:133], v[170:173], 0
	v_mfma_f32_16x16x32_f16 v[106:109], v[148:151], v[170:173], 0
	v_mfma_f32_16x16x32_f16 v[94:97], v[130:133], v[178:181], 0
	v_mfma_f32_16x16x32_f16 v[90:93], v[148:151], v[178:181], 0
	v_mfma_f32_16x16x32_f16 v[78:81], v[130:133], v[186:189], 0
	v_mfma_f32_16x16x32_f16 v[74:77], v[148:151], v[186:189], 0
	v_mfma_f32_16x16x32_f16 v[126:129], v[134:137], v[166:169], v[126:129]
	v_mfma_f32_16x16x32_f16 v[122:125], v[158:161], v[166:169], v[122:125]
	v_mfma_f32_16x16x32_f16 v[110:113], v[134:137], v[174:177], v[110:113]
	v_mfma_f32_16x16x32_f16 v[106:109], v[158:161], v[174:177], v[106:109]
	v_mfma_f32_16x16x32_f16 v[94:97], v[134:137], v[182:185], v[94:97]
	v_mfma_f32_16x16x32_f16 v[90:93], v[158:161], v[182:185], v[90:93]
	v_mfma_f32_16x16x32_f16 v[78:81], v[134:137], v[190:193], v[78:81]
	v_mfma_f32_16x16x32_f16 v[74:77], v[158:161], v[190:193], v[74:77]
	v_mfma_f32_16x16x32_f16 v[118:121], v[194:197], v[162:165], 0
	v_mfma_f32_16x16x32_f16 v[114:117], v[202:205], v[162:165], 0
	v_mfma_f32_16x16x32_f16 v[102:105], v[194:197], v[170:173], 0
	v_mfma_f32_16x16x32_f16 v[98:101], v[202:205], v[170:173], 0
	v_mfma_f32_16x16x32_f16 v[86:89], v[194:197], v[178:181], 0
	v_mfma_f32_16x16x32_f16 v[82:85], v[202:205], v[178:181], 0
	v_mfma_f32_16x16x32_f16 v[70:73], v[194:197], v[186:189], 0
	v_mfma_f32_16x16x32_f16 v[66:69], v[202:205], v[186:189], 0
	v_mfma_f32_16x16x32_f16 v[118:121], v[198:201], v[166:169], v[118:121]
	v_mfma_f32_16x16x32_f16 v[114:117], v[220:223], v[166:169], v[114:117]
	v_mfma_f32_16x16x32_f16 v[102:105], v[198:201], v[174:177], v[102:105]
	v_mfma_f32_16x16x32_f16 v[98:101], v[220:223], v[174:177], v[98:101]
	v_mfma_f32_16x16x32_f16 v[86:89], v[198:201], v[182:185], v[86:89]
	v_mfma_f32_16x16x32_f16 v[82:85], v[220:223], v[182:185], v[82:85]
	v_mfma_f32_16x16x32_f16 v[70:73], v[198:201], v[190:193], v[70:73]
	v_mfma_f32_16x16x32_f16 v[66:69], v[220:223], v[190:193], v[66:69]
	s_barrier
	v_lshl_add_u64 v[152:153], s[40:41], 0, v[0:1]
	s_mov_b32 m0, s45
	v_lshl_add_u64 v[206:207], s[40:41], 0, v[142:143]
	global_load_lds_dwordx4 v[152:153], off
	s_add_i32 m0, s45, 0x2000
	s_nop 0
	global_load_lds_dwordx4 v[206:207], off
	s_mov_b32 m0, s23
	v_lshl_add_u64 v[212:213], s[48:49], 0, v[138:139]
	ds_read_b128 v[162:165], v157 offset:16384
	ds_read_b128 v[166:169], v157 offset:17408
	ds_read_b128 v[170:173], v157 offset:18432
	ds_read_b128 v[174:177], v157 offset:19456
	ds_read_b128 v[178:181], v157 offset:20480
	ds_read_b128 v[182:185], v157 offset:21504
	ds_read_b128 v[186:189], v157 offset:22528
	ds_read_b128 v[190:193], v157 offset:23552
	global_load_lds_dwordx4 v[212:213], off
	v_lshl_add_u64 v[224:225], s[48:49], 0, v[140:141]
	s_mov_b32 m0, s27
	s_nop 0
	global_load_lds_dwordx4 v[224:225], off
	s_add_u32 s50, s40, 0x80000
	s_addc_u32 s51, s41, 0
	s_add_i32 s45, s60, s72
	v_lshl_add_u64 v[232:233], s[50:51], 0, v[0:1]
	s_mov_b32 m0, s45
	s_nop 0
	global_load_lds_dwordx4 v[232:233], off
	v_lshl_add_u64 v[232:233], s[50:51], 0, v[142:143]
	s_add_i32 m0, s45, 0x2000
	s_nop 0
	global_load_lds_dwordx4 v[232:233], off
	s_waitcnt vmcnt(8) lgkmcnt(0)
	s_barrier
; #define PG8_STAGE(bufoff, gbase, voff) do { _Pragma("unroll") for (int _i = 0; _i < 2; ++_i) \
;         __builtin_amdgcn_global_load_lds((const unsigned*)((const char*)(gbase) + (voff)[_i]), (LAS unsigned*)(lds + (bufoff) + ldsw + _i * 8192), 16, 0, 0); } while (0)
; #define PG8_LDA(dst, b, h) do { _Pragma("unroll") for (int m = 0; m < 4; ++m) _Pragma("unroll") for (int k = 0; k < 2; ++k) dst[m][k] = *(const LAS h16x8*)(lds + PG8_SA(b, h) + aoff + m * 2048 + k * 1024); } while (0)
; #define PG8_LDB(dst, b, h) do { _Pragma("unroll") for (int n = 0; n < 2; ++n) _Pragma("unroll") for (int k = 0; k < 2; ++k) dst[n][k] = *(const LAS h16x8*)(lds + PG8_SB(b, h) + boff + n * 2048 + k * 1024); } while (0)
; #define PG8_MMA(ai, bj, At, Bt_) do { __builtin_amdgcn_s_setprio(1); _Pragma("unroll") for (int m = 0; m < 4; ++m) _Pragma("unroll") for (int n = 0; n < 2; ++n) _Pragma("unroll") for (int k = 0; k < 2; ++k) \
;         acc[ai][bj][m][n] = __builtin_amdgcn_mfma_f32_16x16x32_f16(Bt_[n][k], At[m][k], acc[ai][bj][m][n], 0, 0, 0); __builtin_amdgcn_s_setprio(0); } while (0)
; #define PG8_WAIT_V(n) asm volatile("s_waitcnt vmcnt(" #n ")" ::: "memory")
; #define PG8_WAIT_L(n) asm volatile("s_waitcnt lgkmcnt(" #n ")" ::: "memory")
; #define PG8_BAR __builtin_amdgcn_s_barrier()
; #define PG8_SCHED __builtin_amdgcn_sched_barrier(0)
; template <class Epi, class AMap>
; __device__ __forceinline__ void gemm_phase(LAS unsigned char* lds, const AMap am, const int lda, const h16* Bt, const int ldb, const int M, const int N, const int K, const Epi& E) {
;     ...
;             PG8_WAIT_V(6); PG8_BAR; PG8_MMA(1, 1, At, B1); PG8_BAR;
;             PG8_LDB(B0, 1, 0); PG8_SCHED; PG8_LDA(At, 1, 0); PG8_STAGE(PG8_SA(0, 1), a2 + hstepA, voffA);
;             PG8_WAIT_L(8); PG8_BAR; PG8_WAIT_L(0); PG8_MMA(0, 0, At, B0); PG8_BAR; PG8_SCHED;
;             PG8_LDB(B1, 1, 1); PG8_STAGE(PG8_SB(1, 0), b3, voffB);
;             PG8_BAR; PG8_WAIT_L(0); PG8_MMA(0, 1, At, B1); PG8_BAR;
	v_mfma_f32_16x16x32_f16 v[62:65], v[130:133], v[162:165], 0
	v_mfma_f32_16x16x32_f16 v[58:61], v[148:151], v[162:165], 0
	v_mfma_f32_16x16x32_f16 v[46:49], v[130:133], v[170:173], 0
	v_mfma_f32_16x16x32_f16 v[42:45], v[148:151], v[170:173], 0
	v_mfma_f32_16x16x32_f16 v[30:33], v[130:133], v[178:181], 0
	v_mfma_f32_16x16x32_f16 v[26:29], v[148:151], v[178:181], 0
	v_mfma_f32_16x16x32_f16 v[14:17], v[130:133], v[186:189], 0
	v_mfma_f32_16x16x32_f16 v[10:13], v[148:151], v[186:189], 0
	v_mfma_f32_16x16x32_f16 v[62:65], v[134:137], v[166:169], v[62:65]
	v_mfma_f32_16x16x32_f16 v[58:61], v[158:161], v[166:169], v[58:61]
	v_mfma_f32_16x16x32_f16 v[46:49], v[134:137], v[174:177], v[46:49]
	v_mfma_f32_16x16x32_f16 v[42:45], v[158:161], v[174:177], v[42:45]
	v_mfma_f32_16x16x32_f16 v[30:33], v[134:137], v[182:185], v[30:33]
	v_mfma_f32_16x16x32_f16 v[26:29], v[158:161], v[182:185], v[26:29]
	v_mfma_f32_16x16x32_f16 v[14:17], v[134:137], v[190:193], v[14:17]
	v_mfma_f32_16x16x32_f16 v[10:13], v[158:161], v[190:193], v[10:13]
	v_mfma_f32_16x16x32_f16 v[54:57], v[194:197], v[162:165], 0
	v_mfma_f32_16x16x32_f16 v[50:53], v[202:205], v[162:165], 0
	v_mfma_f32_16x16x32_f16 v[38:41], v[194:197], v[170:173], 0
	v_mfma_f32_16x16x32_f16 v[34:37], v[202:205], v[170:173], 0
	v_mfma_f32_16x16x32_f16 v[22:25], v[194:197], v[178:181], 0
	v_mfma_f32_16x16x32_f16 v[18:21], v[202:205], v[178:181], 0
	v_mfma_f32_16x16x32_f16 v[6:9], v[194:197], v[186:189], 0
	v_mfma_f32_16x16x32_f16 v[2:5], v[202:205], v[186:189], 0
	v_mfma_f32_16x16x32_f16 v[54:57], v[198:201], v[166:169], v[54:57]
	v_mfma_f32_16x16x32_f16 v[50:53], v[220:223], v[166:169], v[50:53]
	v_mfma_f32_16x16x32_f16 v[38:41], v[198:201], v[174:177], v[38:41]
	v_mfma_f32_16x16x32_f16 v[34:37], v[220:223], v[174:177], v[34:37]
	v_mfma_f32_16x16x32_f16 v[22:25], v[198:201], v[182:185], v[22:25]
	v_mfma_f32_16x16x32_f16 v[18:21], v[220:223], v[182:185], v[18:21]
	v_mfma_f32_16x16x32_f16 v[6:9], v[198:201], v[190:193], v[6:9]
	v_mfma_f32_16x16x32_f16 v[2:5], v[220:223], v[190:193], v[2:5]
	s_barrier
	s_add_i32 s45, 0, 0x18000
	v_add_u32_e32 v234, s45, v155
	ds_read_b128 v[130:133], v234
	ds_read_b128 v[134:137], v234 offset:1024
	ds_read_b128 v[148:151], v234 offset:2048
	ds_read_b128 v[158:161], v234 offset:3072
	s_add_u32 s48, s48, 0x80000
	s_addc_u32 s49, s49, 0
	s_mov_b32 m0, s73
	v_lshl_add_u64 v[232:233], s[48:49], 0, v[138:139]
	ds_read_b128 v[162:165], v157 offset:32768
	ds_read_b128 v[166:169], v157 offset:33792
	ds_read_b128 v[170:173], v157 offset:34816
	ds_read_b128 v[174:177], v157 offset:35840
	ds_read_b128 v[178:181], v157 offset:36864
	ds_read_b128 v[182:185], v157 offset:37888
	ds_read_b128 v[186:189], v157 offset:38912
	ds_read_b128 v[190:193], v157 offset:39936
	global_load_lds_dwordx4 v[232:233], off
	v_lshl_add_u64 v[232:233], s[48:49], 0, v[140:141]
	s_mov_b32 m0, s74
	s_nop 0
	global_load_lds_dwordx4 v[232:233], off
	s_waitcnt lgkmcnt(11)
	s_add_i32 s48, 0, 0x1c000
	s_add_i32 s45, s45, s72
	v_add_u32_e32 v214, s48, v155
	v_lshl_add_u64 v[152:153], v[152:153], 0, s[92:93]
	s_mov_b32 m0, s45
	ds_read_b128 v[194:197], v214
	ds_read_b128 v[198:201], v214 offset:1024
	ds_read_b128 v[202:205], v214 offset:2048
	ds_read_b128 v[220:223], v214 offset:3072
	s_waitcnt vmcnt(8) lgkmcnt(0)
	s_barrier
	v_mfma_f32_16x16x32_f16 v[126:129], v[130:133], v[162:165], v[126:129]
	v_mfma_f32_16x16x32_f16 v[122:125], v[148:151], v[162:165], v[122:125]
	v_mfma_f32_16x16x32_f16 v[110:113], v[130:133], v[170:173], v[110:113]
	v_mfma_f32_16x16x32_f16 v[106:109], v[148:151], v[170:173], v[106:109]
	v_mfma_f32_16x16x32_f16 v[94:97], v[130:133], v[178:181], v[94:97]
	v_mfma_f32_16x16x32_f16 v[90:93], v[148:151], v[178:181], v[90:93]
	v_mfma_f32_16x16x32_f16 v[78:81], v[130:133], v[186:189], v[78:81]
	v_mfma_f32_16x16x32_f16 v[74:77], v[148:151], v[186:189], v[74:77]
	v_mfma_f32_16x16x32_f16 v[126:129], v[134:137], v[166:169], v[126:129]
	v_mfma_f32_16x16x32_f16 v[122:125], v[158:161], v[166:169], v[122:125]
	v_mfma_f32_16x16x32_f16 v[110:113], v[134:137], v[174:177], v[110:113]
	v_mfma_f32_16x16x32_f16 v[106:109], v[158:161], v[174:177], v[106:109]
	v_mfma_f32_16x16x32_f16 v[94:97], v[134:137], v[182:185], v[94:97]
	v_mfma_f32_16x16x32_f16 v[90:93], v[158:161], v[182:185], v[90:93]
	v_mfma_f32_16x16x32_f16 v[78:81], v[134:137], v[190:193], v[78:81]
	v_mfma_f32_16x16x32_f16 v[74:77], v[158:161], v[190:193], v[74:77]
	v_mfma_f32_16x16x32_f16 v[118:121], v[194:197], v[162:165], v[118:121]
	v_mfma_f32_16x16x32_f16 v[114:117], v[202:205], v[162:165], v[114:117]
	v_mfma_f32_16x16x32_f16 v[102:105], v[194:197], v[170:173], v[102:105]
	v_mfma_f32_16x16x32_f16 v[98:101], v[202:205], v[170:173], v[98:101]
	v_mfma_f32_16x16x32_f16 v[86:89], v[194:197], v[178:181], v[86:89]
	v_mfma_f32_16x16x32_f16 v[82:85], v[202:205], v[178:181], v[82:85]
	v_mfma_f32_16x16x32_f16 v[70:73], v[194:197], v[186:189], v[70:73]
	v_mfma_f32_16x16x32_f16 v[66:69], v[202:205], v[186:189], v[66:69]
	v_mfma_f32_16x16x32_f16 v[118:121], v[198:201], v[166:169], v[118:121]
	v_mfma_f32_16x16x32_f16 v[114:117], v[220:223], v[166:169], v[114:117]
	v_mfma_f32_16x16x32_f16 v[102:105], v[198:201], v[174:177], v[102:105]
	v_mfma_f32_16x16x32_f16 v[98:101], v[220:223], v[174:177], v[98:101]
	v_mfma_f32_16x16x32_f16 v[86:89], v[198:201], v[182:185], v[86:89]
	v_mfma_f32_16x16x32_f16 v[82:85], v[220:223], v[182:185], v[82:85]
	v_mfma_f32_16x16x32_f16 v[70:73], v[198:201], v[190:193], v[70:73]
	v_mfma_f32_16x16x32_f16 v[66:69], v[220:223], v[190:193], v[66:69]
	s_barrier
; #define PG8_STAGE(bufoff, gbase, voff) do { _Pragma("unroll") for (int _i = 0; _i < 2; ++_i) \
;         __builtin_amdgcn_global_load_lds((const unsigned*)((const char*)(gbase) + (voff)[_i]), (LAS unsigned*)(lds + (bufoff) + ldsw + _i * 8192), 16, 0, 0); } while (0)
; #define PG8_LDA(dst, b, h) do { _Pragma("unroll") for (int m = 0; m < 4; ++m) _Pragma("unroll") for (int k = 0; k < 2; ++k) dst[m][k] = *(const LAS h16x8*)(lds + PG8_SA(b, h) + aoff + m * 2048 + k * 1024); } while (0)
; #define PG8_MMA(ai, bj, At, Bt_) do { __builtin_amdgcn_s_setprio(1); _Pragma("unroll") for (int m = 0; m < 4; ++m) _Pragma("unroll") for (int n = 0; n < 2; ++n) _Pragma("unroll") for (int k = 0; k < 2; ++k) \
;         acc[ai][bj][m][n] = __builtin_amdgcn_mfma_f32_16x16x32_f16(Bt_[n][k], At[m][k], acc[ai][bj][m][n], 0, 0, 0); __builtin_amdgcn_s_setprio(0); } while (0)
; #define PG8_WAIT_V(n) asm volatile("s_waitcnt vmcnt(" #n ")" ::: "memory")
; #define PG8_WAIT_L(n) asm volatile("s_waitcnt lgkmcnt(" #n ")" ::: "memory")
; #define PG8_BAR __builtin_amdgcn_s_barrier()
; #define PG8_SCHED __builtin_amdgcn_sched_barrier(0)
; template <class Epi, class AMap>
; __device__ __forceinline__ void gemm_phase(LAS unsigned char* lds, const AMap am, const int lda, const h16* Bt, const int ldb, const int M, const int N, const int K, const Epi& E) {
;     ...
;             PG8_LDA(At, 1, 1); PG8_STAGE(PG8_SA(1, 0), a3, voffA);
;             PG8_BAR; PG8_WAIT_L(0); PG8_MMA(1, 0, At, B0); PG8_BAR; PG8_SCHED;
;             PG8_STAGE(PG8_SB(1, 1), b3 + hstepB, voffB);
;             PG8_WAIT_V(6); PG8_BAR; PG8_MMA(1, 1, At, B1); PG8_BAR;
;         }
	global_load_lds_dwordx4 v[152:153], off
	v_lshl_add_u64 v[152:153], v[206:207], 0, s[92:93]
	s_add_i32 m0, s45, 0x2000
	s_nop 0
	global_load_lds_dwordx4 v[152:153], off
	s_mov_b32 m0, s75
	v_lshl_add_u64 v[152:153], v[212:213], 0, s[92:93]
	ds_read_b128 v[162:165], v157 offset:49152
	ds_read_b128 v[166:169], v157 offset:50176
	ds_read_b128 v[170:173], v157 offset:51200
	ds_read_b128 v[174:177], v157 offset:52224
	ds_read_b128 v[178:181], v157 offset:53248
	ds_read_b128 v[182:185], v157 offset:54272
	ds_read_b128 v[186:189], v157 offset:55296
	ds_read_b128 v[190:193], v157 offset:56320
	global_load_lds_dwordx4 v[152:153], off
	v_lshl_add_u64 v[152:153], v[224:225], 0, s[92:93]
	s_mov_b32 m0, s76
	s_nop 0
	global_load_lds_dwordx4 v[152:153], off
	s_add_u32 s40, s40, 0x80080
	s_addc_u32 s41, s41, 0
	s_add_i32 s45, s48, s72
	v_lshl_add_u64 v[232:233], s[40:41], 0, v[0:1]
	s_mov_b32 m0, s45
	s_nop 0
	global_load_lds_dwordx4 v[232:233], off
	v_lshl_add_u64 v[232:233], s[40:41], 0, v[142:143]
	s_add_i32 m0, s45, 0x2000
	s_nop 0
	global_load_lds_dwordx4 v[232:233], off
	s_add_i32 s43, s43, 2
	s_add_u32 s0, s0, 0x100
	s_addc_u32 s1, s1, 0
	s_add_u32 s21, s21, 0x100
	s_addc_u32 s35, s35, 0
	s_cmp_gt_u32 s43, 29
	s_waitcnt vmcnt(8) lgkmcnt(0)
	s_barrier
	v_mfma_f32_16x16x32_f16 v[62:65], v[130:133], v[162:165], v[62:65]
	v_mfma_f32_16x16x32_f16 v[58:61], v[148:151], v[162:165], v[58:61]
	v_mfma_f32_16x16x32_f16 v[46:49], v[130:133], v[170:173], v[46:49]
	v_mfma_f32_16x16x32_f16 v[42:45], v[148:151], v[170:173], v[42:45]
	v_mfma_f32_16x16x32_f16 v[30:33], v[130:133], v[178:181], v[30:33]
	v_mfma_f32_16x16x32_f16 v[26:29], v[148:151], v[178:181], v[26:29]
	v_mfma_f32_16x16x32_f16 v[14:17], v[130:133], v[186:189], v[14:17]
	v_mfma_f32_16x16x32_f16 v[10:13], v[148:151], v[186:189], v[10:13]
	v_mfma_f32_16x16x32_f16 v[62:65], v[134:137], v[166:169], v[62:65]
	v_mfma_f32_16x16x32_f16 v[58:61], v[158:161], v[166:169], v[58:61]
	v_mfma_f32_16x16x32_f16 v[46:49], v[134:137], v[174:177], v[46:49]
	v_mfma_f32_16x16x32_f16 v[42:45], v[158:161], v[174:177], v[42:45]
	v_mfma_f32_16x16x32_f16 v[30:33], v[134:137], v[182:185], v[30:33]
	v_mfma_f32_16x16x32_f16 v[26:29], v[158:161], v[182:185], v[26:29]
	v_mfma_f32_16x16x32_f16 v[14:17], v[134:137], v[190:193], v[14:17]
	v_mfma_f32_16x16x32_f16 v[10:13], v[158:161], v[190:193], v[10:13]
	v_mfma_f32_16x16x32_f16 v[54:57], v[194:197], v[162:165], v[54:57]
	v_mfma_f32_16x16x32_f16 v[50:53], v[202:205], v[162:165], v[50:53]
	v_mfma_f32_16x16x32_f16 v[38:41], v[194:197], v[170:173], v[38:41]
	v_mfma_f32_16x16x32_f16 v[34:37], v[202:205], v[170:173], v[34:37]
	v_mfma_f32_16x16x32_f16 v[22:25], v[194:197], v[178:181], v[22:25]
	v_mfma_f32_16x16x32_f16 v[18:21], v[202:205], v[178:181], v[18:21]
	v_mfma_f32_16x16x32_f16 v[6:9], v[194:197], v[186:189], v[6:9]
	v_mfma_f32_16x16x32_f16 v[2:5], v[202:205], v[186:189], v[2:5]
	v_mfma_f32_16x16x32_f16 v[54:57], v[198:201], v[166:169], v[54:57]
	v_mfma_f32_16x16x32_f16 v[50:53], v[220:223], v[166:169], v[50:53]
	v_mfma_f32_16x16x32_f16 v[38:41], v[198:201], v[174:177], v[38:41]
	v_mfma_f32_16x16x32_f16 v[34:37], v[220:223], v[174:177], v[34:37]
	v_mfma_f32_16x16x32_f16 v[22:25], v[198:201], v[182:185], v[22:25]
	v_mfma_f32_16x16x32_f16 v[18:21], v[220:223], v[182:185], v[18:21]
	v_mfma_f32_16x16x32_f16 v[6:9], v[198:201], v[190:193], v[6:9]
	v_mfma_f32_16x16x32_f16 v[2:5], v[220:223], v[190:193], v[2:5]
	s_barrier
	s_cbranch_scc1 .Lg4x_799
